# v75 + K-loops: per-trip LDS fragment address adds replaced by one loop-invariant VGPR and ds_read offset immediates
# speedup vs baseline: 1.0025x; 1.0025x over previous
.LBB0_266:
	s_xor_b64 s[2:3], s[2:3], -1
	s_mov_b32 s34, s74
	s_add_i32 s74, s74, 1
	s_cmp_lt_u32 s34, 5
	s_mov_b64 s[4:5], s[10:11]
	s_mov_b32 s10, s75
	s_cselect_b64 s[14:15], -1, 0
	s_add_i32 s75, s74, s16
	s_mov_b64 s[12:13], s[8:9]
	s_and_b64 s[8:9], s[14:15], exec
	s_cselect_b32 s8, s75, s10
	s_cselect_b32 s10, s6, s6
	s_ashr_i32 s11, s10, 31
	s_lshl_b64 s[10:11], s[10:11], 19
	s_add_u32 s10, s80, s10
	s_addc_u32 s11, s81, s11
	s_and_b64 s[44:45], s[14:15], exec
	s_cselect_b32 s44, s11, s5
	s_cselect_b32 s45, s10, s4
	s_ashr_i32 s9, s8, 31
	s_lshl_b64 s[8:9], s[8:9], 19
	v_readlane_b32 s47, v255, 14
	s_add_u32 s8, s47, s8
	v_readlane_b32 s47, v255, 15
	s_addc_u32 s9, s47, s9
	s_and_b64 s[14:15], s[14:15], exec
	s_cselect_b32 s47, s9, s13
	s_cselect_b32 s55, s8, s12
	s_add_u32 s4, s4, 0x40080
	s_addc_u32 s5, s5, 0
	s_add_u32 s78, s12, 0x100
	v_mov_b32_e32 v2, 0
	s_addc_u32 s79, s13, 0
	s_mov_b32 s85, -2
	v_mov_b32_e32 v3, v2
	s_waitcnt lgkmcnt(0)
	v_mov_b32_e32 v4, v2
	v_mov_b32_e32 v5, v2
	v_mov_b32_e32 v6, v2
	v_mov_b32_e32 v7, v2
	v_mov_b32_e32 v8, v2
	v_mov_b32_e32 v9, v2
	v_mov_b32_e32 v18, v2
	v_mov_b32_e32 v19, v2
	v_mov_b32_e32 v20, v2
	v_mov_b32_e32 v21, v2
	v_mov_b32_e32 v22, v2
	v_mov_b32_e32 v23, v2
	v_mov_b32_e32 v24, v2
	v_mov_b32_e32 v25, v2
	v_mov_b32_e32 v34, v2
	v_mov_b32_e32 v35, v2
	v_mov_b32_e32 v36, v2
	v_mov_b32_e32 v37, v2
	v_mov_b32_e32 v38, v2
	v_mov_b32_e32 v39, v2
	v_mov_b32_e32 v40, v2
	v_mov_b32_e32 v41, v2
	v_mov_b32_e32 v50, v2
	v_mov_b32_e32 v51, v2
	v_mov_b32_e32 v52, v2
	v_mov_b32_e32 v53, v2
	v_mov_b32_e32 v54, v2
	v_mov_b32_e32 v55, v2
	v_mov_b32_e32 v56, v2
	v_mov_b32_e32 v57, v2
	v_mov_b32_e32 v10, v2
	v_mov_b32_e32 v11, v2
	v_mov_b32_e32 v12, v2
	v_mov_b32_e32 v13, v2
	v_mov_b32_e32 v14, v2
	v_mov_b32_e32 v15, v2
	v_mov_b32_e32 v16, v2
	v_mov_b32_e32 v17, v2
	v_mov_b32_e32 v26, v2
	v_mov_b32_e32 v27, v2
	v_mov_b32_e32 v28, v2
	v_mov_b32_e32 v29, v2
	v_mov_b32_e32 v30, v2
	v_mov_b32_e32 v31, v2
	v_mov_b32_e32 v32, v2
	v_mov_b32_e32 v33, v2
	v_mov_b32_e32 v42, v2
	v_mov_b32_e32 v43, v2
	v_mov_b32_e32 v44, v2
	v_mov_b32_e32 v45, v2
	v_mov_b32_e32 v46, v2
	v_mov_b32_e32 v47, v2
	v_mov_b32_e32 v48, v2
	v_mov_b32_e32 v49, v2
	v_mov_b32_e32 v58, v2
	v_mov_b32_e32 v59, v2
	v_mov_b32_e32 v60, v2
	v_mov_b32_e32 v61, v2
	v_mov_b32_e32 v62, v2
	v_mov_b32_e32 v63, v2
	v_mov_b32_e32 v64, v2
	v_mov_b32_e32 v65, v2
	v_mov_b32_e32 v66, v2
	v_mov_b32_e32 v67, v2
	v_mov_b32_e32 v68, v2
	v_mov_b32_e32 v69, v2
	v_mov_b32_e32 v70, v2
	v_mov_b32_e32 v71, v2
	v_mov_b32_e32 v72, v2
	v_mov_b32_e32 v73, v2
	v_mov_b32_e32 v82, v2
	v_mov_b32_e32 v83, v2
	v_mov_b32_e32 v84, v2
	v_mov_b32_e32 v85, v2
	v_mov_b32_e32 v86, v2
	v_mov_b32_e32 v87, v2
	v_mov_b32_e32 v88, v2
	v_mov_b32_e32 v89, v2
	v_mov_b32_e32 v98, v2
	v_mov_b32_e32 v99, v2
	v_mov_b32_e32 v100, v2
	v_mov_b32_e32 v101, v2
	v_mov_b32_e32 v102, v2
	v_mov_b32_e32 v103, v2
	v_mov_b32_e32 v104, v2
	v_mov_b32_e32 v105, v2
	v_mov_b32_e32 v114, v2
	v_mov_b32_e32 v115, v2
	v_mov_b32_e32 v116, v2
	v_mov_b32_e32 v117, v2
	v_mov_b32_e32 v118, v2
	v_mov_b32_e32 v119, v2
	v_mov_b32_e32 v120, v2
	v_mov_b32_e32 v121, v2
	v_mov_b32_e32 v74, v2
	v_mov_b32_e32 v75, v2
	v_mov_b32_e32 v76, v2
	v_mov_b32_e32 v77, v2
	v_mov_b32_e32 v78, v2
	v_mov_b32_e32 v79, v2
	v_mov_b32_e32 v80, v2
	v_mov_b32_e32 v81, v2
	v_mov_b32_e32 v90, v2
	v_mov_b32_e32 v91, v2
	v_mov_b32_e32 v92, v2
	v_mov_b32_e32 v93, v2
	v_mov_b32_e32 v94, v2
	v_mov_b32_e32 v95, v2
	v_mov_b32_e32 v96, v2
	v_mov_b32_e32 v97, v2
	v_mov_b32_e32 v106, v2
	v_mov_b32_e32 v107, v2
	v_mov_b32_e32 v108, v2
	v_mov_b32_e32 v109, v2
	v_mov_b32_e32 v110, v2
	v_mov_b32_e32 v111, v2
	v_mov_b32_e32 v112, v2
	v_mov_b32_e32 v113, v2
	v_mov_b32_e32 v122, v2
	v_mov_b32_e32 v123, v2
	v_mov_b32_e32 v124, v2
	v_mov_b32_e32 v125, v2
	v_mov_b32_e32 v126, v2
	v_mov_b32_e32 v127, v2
	v_mov_b32_e32 v128, v2
	v_mov_b32_e32 v129, v2
	s_add_i32 s86, 0, 0x10000
	v_add_u32_e32 v0, s86, v150
	v_add_u32_e32 v189, 0x10000, v150
	ds_read_b128 v[142:145], v0
	ds_read_b128 v[146:149], v0 offset:1024
	ds_read_b128 v[152:155], v0 offset:2048
	ds_read_b128 v[156:159], v0 offset:3072
	s_add_u32 s12, s4, 0xfffc0080
	s_addc_u32 s13, s5, -1
	s_cmp_eq_u32 s85, 12
	s_cselect_b32 s15, s44, s13
	s_cselect_b32 s14, s45, s12
	s_cselect_b32 s13, s47, s79
	s_cselect_b32 s12, s55, s78
.LBB0_267:
	s_add_i32 m0, s7, 0xc000
	ds_read_b128 v[160:163], v151
	ds_read_b128 v[164:167], v151 offset:1024
	ds_read_b128 v[168:171], v151 offset:2048
	ds_read_b128 v[172:175], v151 offset:3072
	ds_read_b128 v[176:179], v151 offset:4096
	ds_read_b128 v[180:183], v151 offset:5120
	ds_read_b128 v[184:187], v151 offset:6144
	ds_read_b128 v[190:193], v151 offset:7168
	global_load_lds_dwordx4 v138, s[4:5]
	s_add_i32 m0, s7, 0xe000
	s_nop 0
	global_load_lds_dwordx4 v140, s[4:5]
	s_waitcnt lgkmcnt(8)
	s_barrier
	s_waitcnt lgkmcnt(0)
	v_mfma_f32_16x16x32_bf16 v[126:129], v[142:145], v[160:163], v[126:129]
	v_mfma_f32_16x16x32_bf16 v[122:125], v[152:155], v[160:163], v[122:125]
	v_mfma_f32_16x16x32_bf16 v[110:113], v[142:145], v[168:171], v[110:113]
	v_mfma_f32_16x16x32_bf16 v[106:109], v[152:155], v[168:171], v[106:109]
	v_mfma_f32_16x16x32_bf16 v[94:97], v[142:145], v[176:179], v[94:97]
	v_mfma_f32_16x16x32_bf16 v[90:93], v[152:155], v[176:179], v[90:93]
	v_mfma_f32_16x16x32_bf16 v[78:81], v[142:145], v[184:187], v[78:81]
	v_mfma_f32_16x16x32_bf16 v[74:77], v[152:155], v[184:187], v[74:77]
	v_mfma_f32_16x16x32_bf16 v[126:129], v[146:149], v[164:167], v[126:129]
	v_mfma_f32_16x16x32_bf16 v[122:125], v[156:159], v[164:167], v[122:125]
	v_mfma_f32_16x16x32_bf16 v[110:113], v[146:149], v[172:175], v[110:113]
	v_mfma_f32_16x16x32_bf16 v[106:109], v[156:159], v[172:175], v[106:109]
	v_mfma_f32_16x16x32_bf16 v[94:97], v[146:149], v[180:183], v[94:97]
	v_mfma_f32_16x16x32_bf16 v[90:93], v[156:159], v[180:183], v[90:93]
	v_mfma_f32_16x16x32_bf16 v[78:81], v[146:149], v[190:193], v[78:81]
	v_mfma_f32_16x16x32_bf16 v[74:77], v[156:159], v[190:193], v[74:77]
	s_barrier
	s_add_i32 s88, 0, 0x14000
	s_add_i32 s86, s86, s22
	s_mov_b32 m0, s86
	ds_read_b128 v[194:197], v189 offset:16384
	ds_read_b128 v[198:201], v189 offset:17408
	ds_read_b128 v[202:205], v189 offset:18432
	ds_read_b128 v[206:209], v189 offset:19456
	global_load_lds_dwordx4 v134, s[12:13]
	s_add_i32 m0, s86, 0x2000
	s_nop 0
	global_load_lds_dwordx4 v130, s[12:13]
	s_barrier
	s_waitcnt lgkmcnt(0)
	v_mfma_f32_16x16x32_bf16 v[118:121], v[194:197], v[160:163], v[118:121]
	v_mfma_f32_16x16x32_bf16 v[114:117], v[202:205], v[160:163], v[114:117]
	v_mfma_f32_16x16x32_bf16 v[102:105], v[194:197], v[168:171], v[102:105]
	v_mfma_f32_16x16x32_bf16 v[98:101], v[202:205], v[168:171], v[98:101]
	v_mfma_f32_16x16x32_bf16 v[86:89], v[194:197], v[176:179], v[86:89]
	v_mfma_f32_16x16x32_bf16 v[82:85], v[202:205], v[176:179], v[82:85]
	v_mfma_f32_16x16x32_bf16 v[70:73], v[194:197], v[184:187], v[70:73]
	v_mfma_f32_16x16x32_bf16 v[66:69], v[202:205], v[184:187], v[66:69]
	v_mfma_f32_16x16x32_bf16 v[118:121], v[198:201], v[164:167], v[118:121]
	v_mfma_f32_16x16x32_bf16 v[114:117], v[206:209], v[164:167], v[114:117]
	v_mfma_f32_16x16x32_bf16 v[102:105], v[198:201], v[172:175], v[102:105]
	v_mfma_f32_16x16x32_bf16 v[98:101], v[206:209], v[172:175], v[98:101]
	v_mfma_f32_16x16x32_bf16 v[86:89], v[198:201], v[180:183], v[86:89]
	v_mfma_f32_16x16x32_bf16 v[82:85], v[206:209], v[180:183], v[82:85]
	v_mfma_f32_16x16x32_bf16 v[70:73], v[198:201], v[190:193], v[70:73]
	v_mfma_f32_16x16x32_bf16 v[66:69], v[206:209], v[190:193], v[66:69]
	s_mov_b32 m0, s7
	s_mov_b64 s[100:101], s[14:15]
	s_barrier
	ds_read_b128 v[160:163], v151 offset:16384
	ds_read_b128 v[164:167], v151 offset:17408
	ds_read_b128 v[168:171], v151 offset:18432
	ds_read_b128 v[172:175], v151 offset:19456
	ds_read_b128 v[176:179], v151 offset:20480
	ds_read_b128 v[180:183], v151 offset:21504
	ds_read_b128 v[184:187], v151 offset:22528
	ds_read_b128 v[190:193], v151 offset:23552
	global_load_lds_dwordx4 v136, s[100:101]
	s_mov_b32 m0, s23
	s_nop 0
	global_load_lds_dwordx4 v132, s[100:101]
	s_waitcnt vmcnt(10)
	s_barrier
	s_waitcnt lgkmcnt(0)
	v_mfma_f32_16x16x32_bf16 v[62:65], v[142:145], v[160:163], v[62:65]
	v_mfma_f32_16x16x32_bf16 v[58:61], v[152:155], v[160:163], v[58:61]
	v_mfma_f32_16x16x32_bf16 v[46:49], v[142:145], v[168:171], v[46:49]
	v_mfma_f32_16x16x32_bf16 v[42:45], v[152:155], v[168:171], v[42:45]
	v_mfma_f32_16x16x32_bf16 v[30:33], v[142:145], v[176:179], v[30:33]
	v_mfma_f32_16x16x32_bf16 v[26:29], v[152:155], v[176:179], v[26:29]
	v_mfma_f32_16x16x32_bf16 v[14:17], v[142:145], v[184:187], v[14:17]
	v_mfma_f32_16x16x32_bf16 v[10:13], v[152:155], v[184:187], v[10:13]
	v_mfma_f32_16x16x32_bf16 v[62:65], v[146:149], v[164:167], v[62:65]
	v_mfma_f32_16x16x32_bf16 v[58:61], v[156:159], v[164:167], v[58:61]
	v_mfma_f32_16x16x32_bf16 v[46:49], v[146:149], v[172:175], v[46:49]
	v_mfma_f32_16x16x32_bf16 v[42:45], v[156:159], v[172:175], v[42:45]
	v_mfma_f32_16x16x32_bf16 v[30:33], v[146:149], v[180:183], v[30:33]
	v_mfma_f32_16x16x32_bf16 v[26:29], v[156:159], v[180:183], v[26:29]
	v_mfma_f32_16x16x32_bf16 v[14:17], v[146:149], v[190:193], v[14:17]
	v_mfma_f32_16x16x32_bf16 v[10:13], v[156:159], v[190:193], v[10:13]
	s_barrier
	s_add_u32 s86, s12, 0x40000
	s_addc_u32 s87, s13, 0
	s_add_i32 s88, s88, s22
	s_mov_b32 m0, s88
	s_nop 0
	global_load_lds_dwordx4 v134, s[86:87]
	s_add_i32 m0, s88, 0x2000
	s_nop 0
	global_load_lds_dwordx4 v130, s[86:87]
	s_add_i32 s86, 0, 0x18000
	ds_read_b128 v[142:145], v189 offset:32768
	ds_read_b128 v[146:149], v189 offset:33792
	ds_read_b128 v[152:155], v189 offset:34816
	ds_read_b128 v[156:159], v189 offset:35840
	s_waitcnt vmcnt(6)
	s_barrier
	v_mfma_f32_16x16x32_bf16 v[54:57], v[194:197], v[160:163], v[54:57]
	v_mfma_f32_16x16x32_bf16 v[50:53], v[202:205], v[160:163], v[50:53]
	v_mfma_f32_16x16x32_bf16 v[38:41], v[194:197], v[168:171], v[38:41]
	v_mfma_f32_16x16x32_bf16 v[34:37], v[202:205], v[168:171], v[34:37]
	v_mfma_f32_16x16x32_bf16 v[22:25], v[194:197], v[176:179], v[22:25]
	v_mfma_f32_16x16x32_bf16 v[18:21], v[202:205], v[176:179], v[18:21]
	v_mfma_f32_16x16x32_bf16 v[6:9], v[194:197], v[184:187], v[6:9]
	v_mfma_f32_16x16x32_bf16 v[2:5], v[202:205], v[184:187], v[2:5]
	v_mfma_f32_16x16x32_bf16 v[54:57], v[198:201], v[164:167], v[54:57]
	v_mfma_f32_16x16x32_bf16 v[50:53], v[206:209], v[164:167], v[50:53]
	v_mfma_f32_16x16x32_bf16 v[38:41], v[198:201], v[172:175], v[38:41]
	v_mfma_f32_16x16x32_bf16 v[34:37], v[206:209], v[172:175], v[34:37]
	v_mfma_f32_16x16x32_bf16 v[22:25], v[198:201], v[180:183], v[22:25]
	v_mfma_f32_16x16x32_bf16 v[18:21], v[206:209], v[180:183], v[18:21]
	v_mfma_f32_16x16x32_bf16 v[6:9], v[198:201], v[190:193], v[6:9]
	v_mfma_f32_16x16x32_bf16 v[2:5], v[206:209], v[190:193], v[2:5]
	s_barrier
	s_add_u32 s14, s14, 0x40000
	s_addc_u32 s15, s15, 0
	s_mov_b32 m0, s28
	ds_read_b128 v[160:163], v151 offset:32768
	ds_read_b128 v[164:167], v151 offset:33792
	ds_read_b128 v[168:171], v151 offset:34816
	ds_read_b128 v[172:175], v151 offset:35840
	ds_read_b128 v[176:179], v151 offset:36864
	ds_read_b128 v[180:183], v151 offset:37888
	ds_read_b128 v[184:187], v151 offset:38912
	ds_read_b128 v[190:193], v151 offset:39936
	global_load_lds_dwordx4 v136, s[14:15]
	s_mov_b32 m0, s29
	s_nop 0
	global_load_lds_dwordx4 v132, s[14:15]
	s_waitcnt lgkmcnt(8)
	s_barrier
	s_waitcnt lgkmcnt(0)
	v_mfma_f32_16x16x32_bf16 v[126:129], v[142:145], v[160:163], v[126:129]
	v_mfma_f32_16x16x32_bf16 v[122:125], v[152:155], v[160:163], v[122:125]
	v_mfma_f32_16x16x32_bf16 v[110:113], v[142:145], v[168:171], v[110:113]
	v_mfma_f32_16x16x32_bf16 v[106:109], v[152:155], v[168:171], v[106:109]
	v_mfma_f32_16x16x32_bf16 v[94:97], v[142:145], v[176:179], v[94:97]
	v_mfma_f32_16x16x32_bf16 v[90:93], v[152:155], v[176:179], v[90:93]
	v_mfma_f32_16x16x32_bf16 v[78:81], v[142:145], v[184:187], v[78:81]
	v_mfma_f32_16x16x32_bf16 v[74:77], v[152:155], v[184:187], v[74:77]
	v_mfma_f32_16x16x32_bf16 v[126:129], v[146:149], v[164:167], v[126:129]
	v_mfma_f32_16x16x32_bf16 v[122:125], v[156:159], v[164:167], v[122:125]
	v_mfma_f32_16x16x32_bf16 v[110:113], v[146:149], v[172:175], v[110:113]
	v_mfma_f32_16x16x32_bf16 v[106:109], v[156:159], v[172:175], v[106:109]
	v_mfma_f32_16x16x32_bf16 v[94:97], v[146:149], v[180:183], v[94:97]
	v_mfma_f32_16x16x32_bf16 v[90:93], v[156:159], v[180:183], v[90:93]
	v_mfma_f32_16x16x32_bf16 v[78:81], v[146:149], v[190:193], v[78:81]
	v_mfma_f32_16x16x32_bf16 v[74:77], v[156:159], v[190:193], v[74:77]
	s_barrier
	s_add_i32 s14, 0, 0x1c000
	s_add_i32 s15, s86, s22
	s_mov_b32 m0, s15
	ds_read_b128 v[194:197], v189 offset:49152
	ds_read_b128 v[198:201], v189 offset:50176
	ds_read_b128 v[202:205], v189 offset:51200
	ds_read_b128 v[206:209], v189 offset:52224
	s_add_u32 s98, s12, s40
	s_addc_u32 s99, s13, s41
	global_load_lds_dwordx4 v134, s[98:99]
	s_add_i32 m0, s15, 0x2000
	s_add_u32 s98, s12, s40
	s_addc_u32 s99, s13, s41
	global_load_lds_dwordx4 v130, s[98:99]
	s_barrier
	s_waitcnt lgkmcnt(0)
	v_mfma_f32_16x16x32_bf16 v[118:121], v[194:197], v[160:163], v[118:121]
	v_mfma_f32_16x16x32_bf16 v[114:117], v[202:205], v[160:163], v[114:117]
	v_mfma_f32_16x16x32_bf16 v[102:105], v[194:197], v[168:171], v[102:105]
	v_mfma_f32_16x16x32_bf16 v[98:101], v[202:205], v[168:171], v[98:101]
	v_mfma_f32_16x16x32_bf16 v[86:89], v[194:197], v[176:179], v[86:89]
	v_mfma_f32_16x16x32_bf16 v[82:85], v[202:205], v[176:179], v[82:85]
	v_mfma_f32_16x16x32_bf16 v[70:73], v[194:197], v[184:187], v[70:73]
	v_mfma_f32_16x16x32_bf16 v[66:69], v[202:205], v[184:187], v[66:69]
	v_mfma_f32_16x16x32_bf16 v[118:121], v[198:201], v[164:167], v[118:121]
	v_mfma_f32_16x16x32_bf16 v[114:117], v[206:209], v[164:167], v[114:117]
	v_mfma_f32_16x16x32_bf16 v[102:105], v[198:201], v[172:175], v[102:105]
	v_mfma_f32_16x16x32_bf16 v[98:101], v[206:209], v[172:175], v[98:101]
	v_mfma_f32_16x16x32_bf16 v[86:89], v[198:201], v[180:183], v[86:89]
	v_mfma_f32_16x16x32_bf16 v[82:85], v[206:209], v[180:183], v[82:85]
	v_mfma_f32_16x16x32_bf16 v[70:73], v[198:201], v[190:193], v[70:73]
	v_mfma_f32_16x16x32_bf16 v[66:69], v[206:209], v[190:193], v[66:69]
	s_mov_b32 m0, s38
	s_barrier
	ds_read_b128 v[160:163], v151 offset:49152
	ds_read_b128 v[164:167], v151 offset:50176
	ds_read_b128 v[168:171], v151 offset:51200
	ds_read_b128 v[172:175], v151 offset:52224
	ds_read_b128 v[176:179], v151 offset:53248
	ds_read_b128 v[180:183], v151 offset:54272
	ds_read_b128 v[184:187], v151 offset:55296
	ds_read_b128 v[190:193], v151 offset:56320
	s_add_u32 s98, s100, s40
	s_addc_u32 s99, s101, s41
	global_load_lds_dwordx4 v136, s[98:99]
	s_mov_b32 m0, s39
	s_add_u32 s98, s100, s40
	s_addc_u32 s99, s101, s41
	global_load_lds_dwordx4 v132, s[98:99]
	s_waitcnt vmcnt(10)
	s_barrier
	s_waitcnt lgkmcnt(0)
	v_mfma_f32_16x16x32_bf16 v[62:65], v[142:145], v[160:163], v[62:65]
	v_mfma_f32_16x16x32_bf16 v[58:61], v[152:155], v[160:163], v[58:61]
	v_mfma_f32_16x16x32_bf16 v[46:49], v[142:145], v[168:171], v[46:49]
	v_mfma_f32_16x16x32_bf16 v[42:45], v[152:155], v[168:171], v[42:45]
	v_mfma_f32_16x16x32_bf16 v[30:33], v[142:145], v[176:179], v[30:33]
	v_mfma_f32_16x16x32_bf16 v[26:29], v[152:155], v[176:179], v[26:29]
	v_mfma_f32_16x16x32_bf16 v[14:17], v[142:145], v[184:187], v[14:17]
	v_mfma_f32_16x16x32_bf16 v[10:13], v[152:155], v[184:187], v[10:13]
	v_mfma_f32_16x16x32_bf16 v[62:65], v[146:149], v[164:167], v[62:65]
	v_mfma_f32_16x16x32_bf16 v[58:61], v[156:159], v[164:167], v[58:61]
	v_mfma_f32_16x16x32_bf16 v[46:49], v[146:149], v[172:175], v[46:49]
	v_mfma_f32_16x16x32_bf16 v[42:45], v[156:159], v[172:175], v[42:45]
	v_mfma_f32_16x16x32_bf16 v[30:33], v[146:149], v[180:183], v[30:33]
	v_mfma_f32_16x16x32_bf16 v[26:29], v[156:159], v[180:183], v[26:29]
	v_mfma_f32_16x16x32_bf16 v[14:17], v[146:149], v[190:193], v[14:17]
	v_mfma_f32_16x16x32_bf16 v[10:13], v[156:159], v[190:193], v[10:13]
	s_barrier
	s_add_u32 s12, s12, 0x40080
	s_addc_u32 s13, s13, 0
	s_add_i32 s14, s14, s22
	s_mov_b32 m0, s14
	s_nop 0
	global_load_lds_dwordx4 v134, s[12:13]
	s_add_i32 m0, s14, 0x2000
	s_nop 0
	global_load_lds_dwordx4 v130, s[12:13]
	s_add_i32 s86, 0, 0x10000
	ds_read_b128 v[142:145], v189
	ds_read_b128 v[146:149], v189 offset:1024
	ds_read_b128 v[152:155], v189 offset:2048
	ds_read_b128 v[156:159], v189 offset:3072
	s_waitcnt vmcnt(6)
	s_barrier
	v_mfma_f32_16x16x32_bf16 v[54:57], v[194:197], v[160:163], v[54:57]
	v_mfma_f32_16x16x32_bf16 v[50:53], v[202:205], v[160:163], v[50:53]
	v_mfma_f32_16x16x32_bf16 v[38:41], v[194:197], v[168:171], v[38:41]
	v_mfma_f32_16x16x32_bf16 v[34:37], v[202:205], v[168:171], v[34:37]
	v_mfma_f32_16x16x32_bf16 v[22:25], v[194:197], v[176:179], v[22:25]
	v_mfma_f32_16x16x32_bf16 v[18:21], v[202:205], v[176:179], v[18:21]
	v_mfma_f32_16x16x32_bf16 v[6:9], v[194:197], v[184:187], v[6:9]
	v_mfma_f32_16x16x32_bf16 v[2:5], v[202:205], v[184:187], v[2:5]
	v_mfma_f32_16x16x32_bf16 v[54:57], v[198:201], v[164:167], v[54:57]
	v_mfma_f32_16x16x32_bf16 v[50:53], v[206:209], v[164:167], v[50:53]
	v_mfma_f32_16x16x32_bf16 v[38:41], v[198:201], v[172:175], v[38:41]
	v_mfma_f32_16x16x32_bf16 v[34:37], v[206:209], v[172:175], v[34:37]
	v_mfma_f32_16x16x32_bf16 v[22:25], v[198:201], v[180:183], v[22:25]
	v_mfma_f32_16x16x32_bf16 v[18:21], v[206:209], v[180:183], v[18:21]
	v_mfma_f32_16x16x32_bf16 v[6:9], v[198:201], v[190:193], v[6:9]
	v_mfma_f32_16x16x32_bf16 v[2:5], v[206:209], v[190:193], v[2:5]
	s_add_i32 s85, s85, 2
	s_add_u32 s4, s4, 0x100
	s_addc_u32 s5, s5, 0
	s_add_u32 s78, s78, 0x100
	s_addc_u32 s79, s79, 0
	s_add_u32 s12, s4, 0xfffc0080
	s_addc_u32 s13, s5, -1
	s_cmp_eq_u32 s85, 12
	s_cselect_b32 s15, s44, s13
	s_cselect_b32 s14, s45, s12
	s_cselect_b32 s13, s47, s79
	s_cselect_b32 s12, s55, s78
	s_cmp_gt_u32 s85, 13
	s_barrier
	s_cbranch_scc0 .LBB0_267
	s_waitcnt lgkmcnt(0)
	v_mov_b32_e32 v156, v252
	s_mov_b64 s[4:5], -1
	v_and_b32_e32 v154, 63, v156
	s_andn2_b64 vcc, exec, s[2:3]
	v_lshlrev_b32_e32 v142, 2, v154
	s_cbranch_vccnz .LBB0_270
	v_lshlrev_b32_e32 v155, 2, v154
	s_mov_b64 s[4:5], 0

.LBB0_837:
	s_ashr_i32 s15, s14, 31
	s_lshl_b64 s[78:79], s[14:15], 19
	s_add_u32 s84, s36, s78
	s_addc_u32 s85, s37, s79
	s_and_b64 s[4:5], s[4:5], exec
	s_cselect_b32 s15, s85, s91
	s_cselect_b32 s23, s84, s90
	s_add_u32 s34, s90, 0x100
	v_mov_b32_e32 v2, 0
	s_addc_u32 s75, s91, 0
	s_mov_b32 s78, -2
	s_waitcnt lgkmcnt(0)
	v_mov_b32_e32 v3, v2
	v_mov_b32_e32 v4, v2
	v_mov_b32_e32 v5, v2
	v_mov_b32_e32 v6, v2
	v_mov_b32_e32 v7, v2
	v_mov_b32_e32 v8, v2
	v_mov_b32_e32 v9, v2
	v_mov_b32_e32 v18, v2
	v_mov_b32_e32 v19, v2
	v_mov_b32_e32 v20, v2
	v_mov_b32_e32 v21, v2
	v_mov_b32_e32 v22, v2
	v_mov_b32_e32 v23, v2
	v_mov_b32_e32 v24, v2
	v_mov_b32_e32 v25, v2
	v_mov_b32_e32 v34, v2
	v_mov_b32_e32 v35, v2
	v_mov_b32_e32 v36, v2
	v_mov_b32_e32 v37, v2
	v_mov_b32_e32 v38, v2
	v_mov_b32_e32 v39, v2
	v_mov_b32_e32 v40, v2
	v_mov_b32_e32 v41, v2
	v_mov_b32_e32 v50, v2
	v_mov_b32_e32 v51, v2
	v_mov_b32_e32 v52, v2
	v_mov_b32_e32 v53, v2
	v_mov_b32_e32 v54, v2
	v_mov_b32_e32 v55, v2
	v_mov_b32_e32 v56, v2
	v_mov_b32_e32 v57, v2
	v_mov_b32_e32 v10, v2
	v_mov_b32_e32 v11, v2
	v_mov_b32_e32 v12, v2
	v_mov_b32_e32 v13, v2
	v_mov_b32_e32 v14, v2
	v_mov_b32_e32 v15, v2
	v_mov_b32_e32 v16, v2
	v_mov_b32_e32 v17, v2
	v_mov_b32_e32 v26, v2
	v_mov_b32_e32 v27, v2
	v_mov_b32_e32 v28, v2
	v_mov_b32_e32 v29, v2
	v_mov_b32_e32 v30, v2
	v_mov_b32_e32 v31, v2
	v_mov_b32_e32 v32, v2
	v_mov_b32_e32 v33, v2
	v_mov_b32_e32 v42, v2
	v_mov_b32_e32 v43, v2
	v_mov_b32_e32 v44, v2
	v_mov_b32_e32 v45, v2
	v_mov_b32_e32 v46, v2
	v_mov_b32_e32 v47, v2
	v_mov_b32_e32 v48, v2
	v_mov_b32_e32 v49, v2
	v_mov_b32_e32 v58, v2
	v_mov_b32_e32 v59, v2
	v_mov_b32_e32 v60, v2
	v_mov_b32_e32 v61, v2
	v_mov_b32_e32 v62, v2
	v_mov_b32_e32 v63, v2
	v_mov_b32_e32 v64, v2
	v_mov_b32_e32 v65, v2
	v_mov_b32_e32 v66, v2
	v_mov_b32_e32 v67, v2
	v_mov_b32_e32 v68, v2
	v_mov_b32_e32 v69, v2
	v_mov_b32_e32 v70, v2
	v_mov_b32_e32 v71, v2
	v_mov_b32_e32 v72, v2
	v_mov_b32_e32 v73, v2
	v_mov_b32_e32 v82, v2
	v_mov_b32_e32 v83, v2
	v_mov_b32_e32 v84, v2
	v_mov_b32_e32 v85, v2
	v_mov_b32_e32 v86, v2
	v_mov_b32_e32 v87, v2
	v_mov_b32_e32 v88, v2
	v_mov_b32_e32 v89, v2
	v_mov_b32_e32 v98, v2
	v_mov_b32_e32 v99, v2
	v_mov_b32_e32 v100, v2
	v_mov_b32_e32 v101, v2
	v_mov_b32_e32 v102, v2
	v_mov_b32_e32 v103, v2
	v_mov_b32_e32 v104, v2
	v_mov_b32_e32 v105, v2
	v_mov_b32_e32 v114, v2
	v_mov_b32_e32 v115, v2
	v_mov_b32_e32 v116, v2
	v_mov_b32_e32 v117, v2
	v_mov_b32_e32 v118, v2
	v_mov_b32_e32 v119, v2
	v_mov_b32_e32 v120, v2
	v_mov_b32_e32 v121, v2
	v_mov_b32_e32 v74, v2
	v_mov_b32_e32 v75, v2
	v_mov_b32_e32 v76, v2
	v_mov_b32_e32 v77, v2
	v_mov_b32_e32 v78, v2
	v_mov_b32_e32 v79, v2
	v_mov_b32_e32 v80, v2
	v_mov_b32_e32 v81, v2
	v_mov_b32_e32 v90, v2
	v_mov_b32_e32 v91, v2
	v_mov_b32_e32 v92, v2
	v_mov_b32_e32 v93, v2
	v_mov_b32_e32 v94, v2
	v_mov_b32_e32 v95, v2
	v_mov_b32_e32 v96, v2
	v_mov_b32_e32 v97, v2
	v_mov_b32_e32 v106, v2
	v_mov_b32_e32 v107, v2
	v_mov_b32_e32 v108, v2
	v_mov_b32_e32 v109, v2
	v_mov_b32_e32 v110, v2
	v_mov_b32_e32 v111, v2
	v_mov_b32_e32 v112, v2
	v_mov_b32_e32 v113, v2
	v_mov_b32_e32 v122, v2
	v_mov_b32_e32 v123, v2
	v_mov_b32_e32 v124, v2
	v_mov_b32_e32 v125, v2
	v_mov_b32_e32 v126, v2
	v_mov_b32_e32 v127, v2
	v_mov_b32_e32 v128, v2
	v_mov_b32_e32 v129, v2
	s_add_i32 s79, 0, 0x10000
	v_add_u32_e32 v142, s79, v212
	v_add_u32_e32 v189, 0x10000, v212
	ds_read_b128 v[130:133], v142
	ds_read_b128 v[134:137], v142 offset:1024
	ds_read_b128 v[138:141], v142 offset:2048
	ds_read_b128 v[142:145], v142 offset:3072
	s_add_u32 s4, s88, 0x100
	s_addc_u32 s5, s89, 0
	s_cmp_eq_u32 s78, 12
	s_cselect_b32 s93, s17, s5
	s_cselect_b32 s92, s16, s4
	s_cselect_b32 s91, s15, s75
	s_cselect_b32 s90, s23, s34
.LBB0_838:
	v_lshl_add_u64 v[178:179], s[88:89], 0, v[196:197]
	s_add_i32 m0, s39, 0xc000
	ds_read_b128 v[146:149], v213
	ds_read_b128 v[150:153], v213 offset:1024
	ds_read_b128 v[154:157], v213 offset:2048
	ds_read_b128 v[158:161], v213 offset:3072
	ds_read_b128 v[162:165], v213 offset:4096
	ds_read_b128 v[166:169], v213 offset:5120
	ds_read_b128 v[170:173], v213 offset:6144
	ds_read_b128 v[174:177], v213 offset:7168
	global_load_lds_dwordx4 v[178:179], off
	s_add_i32 m0, s39, 0xe000
	v_lshl_add_u64 v[178:179], s[88:89], 0, v[198:199]
	global_load_lds_dwordx4 v[178:179], off
	s_waitcnt lgkmcnt(8)
	s_barrier
	s_waitcnt lgkmcnt(0)
	v_mfma_f32_16x16x32_bf16 v[126:129], v[130:133], v[146:149], v[126:129]
	v_mfma_f32_16x16x32_bf16 v[122:125], v[138:141], v[146:149], v[122:125]
	v_mfma_f32_16x16x32_bf16 v[110:113], v[130:133], v[154:157], v[110:113]
	v_mfma_f32_16x16x32_bf16 v[106:109], v[138:141], v[154:157], v[106:109]
	v_mfma_f32_16x16x32_bf16 v[94:97], v[130:133], v[162:165], v[94:97]
	v_mfma_f32_16x16x32_bf16 v[90:93], v[138:141], v[162:165], v[90:93]
	v_mfma_f32_16x16x32_bf16 v[78:81], v[130:133], v[170:173], v[78:81]
	v_mfma_f32_16x16x32_bf16 v[74:77], v[138:141], v[170:173], v[74:77]
	v_mfma_f32_16x16x32_bf16 v[126:129], v[134:137], v[150:153], v[126:129]
	v_mfma_f32_16x16x32_bf16 v[122:125], v[142:145], v[150:153], v[122:125]
	v_mfma_f32_16x16x32_bf16 v[110:113], v[134:137], v[158:161], v[110:113]
	v_mfma_f32_16x16x32_bf16 v[106:109], v[142:145], v[158:161], v[106:109]
	v_mfma_f32_16x16x32_bf16 v[94:97], v[134:137], v[166:169], v[94:97]
	v_mfma_f32_16x16x32_bf16 v[90:93], v[142:145], v[166:169], v[90:93]
	v_mfma_f32_16x16x32_bf16 v[78:81], v[134:137], v[174:177], v[78:81]
	v_mfma_f32_16x16x32_bf16 v[74:77], v[142:145], v[174:177], v[74:77]
	s_barrier
	s_add_i32 s87, 0, 0x14000
	s_add_i32 s79, s79, s38
	ds_read_b128 v[178:181], v189 offset:16384
	ds_read_b128 v[182:185], v189 offset:17408
	ds_read_b128 v[200:203], v189 offset:18432
	ds_read_b128 v[204:207], v189 offset:19456
	s_mov_b32 m0, s79
	global_load_lds_dwordx4 v0, s[90:91]
	s_add_i32 m0, s79, 0x2000
	s_nop 0
	global_load_lds_dwordx4 v194, s[90:91]
	s_barrier
	s_waitcnt lgkmcnt(0)
	v_mfma_f32_16x16x32_bf16 v[118:121], v[178:181], v[146:149], v[118:121]
	v_mfma_f32_16x16x32_bf16 v[114:117], v[200:203], v[146:149], v[114:117]
	v_mfma_f32_16x16x32_bf16 v[102:105], v[178:181], v[154:157], v[102:105]
	v_mfma_f32_16x16x32_bf16 v[98:101], v[200:203], v[154:157], v[98:101]
	v_mfma_f32_16x16x32_bf16 v[86:89], v[178:181], v[162:165], v[86:89]
	v_mfma_f32_16x16x32_bf16 v[82:85], v[200:203], v[162:165], v[82:85]
	v_mfma_f32_16x16x32_bf16 v[70:73], v[178:181], v[170:173], v[70:73]
	v_mfma_f32_16x16x32_bf16 v[66:69], v[200:203], v[170:173], v[66:69]
	v_mfma_f32_16x16x32_bf16 v[118:121], v[182:185], v[150:153], v[118:121]
	v_mfma_f32_16x16x32_bf16 v[114:117], v[204:207], v[150:153], v[114:117]
	v_mfma_f32_16x16x32_bf16 v[102:105], v[182:185], v[158:161], v[102:105]
	v_mfma_f32_16x16x32_bf16 v[98:101], v[204:207], v[158:161], v[98:101]
	v_mfma_f32_16x16x32_bf16 v[86:89], v[182:185], v[166:169], v[86:89]
	v_mfma_f32_16x16x32_bf16 v[82:85], v[204:207], v[166:169], v[82:85]
	v_mfma_f32_16x16x32_bf16 v[70:73], v[182:185], v[174:177], v[70:73]
	v_mfma_f32_16x16x32_bf16 v[66:69], v[204:207], v[174:177], v[66:69]
	s_mov_b32 m0, s39
	s_barrier
	ds_read_b128 v[146:149], v213 offset:16384
	ds_read_b128 v[150:153], v213 offset:17408
	ds_read_b128 v[154:157], v213 offset:18432
	ds_read_b128 v[158:161], v213 offset:19456
	ds_read_b128 v[162:165], v213 offset:20480
	ds_read_b128 v[166:169], v213 offset:21504
	ds_read_b128 v[170:173], v213 offset:22528
	ds_read_b128 v[174:177], v213 offset:23552
	global_load_lds_dwordx4 v190, s[92:93]
	s_mov_b32 m0, s42
	s_nop 0
	global_load_lds_dwordx4 v192, s[92:93]
	s_waitcnt vmcnt(10)
	s_barrier
	s_waitcnt lgkmcnt(0)
	v_mfma_f32_16x16x32_bf16 v[62:65], v[130:133], v[146:149], v[62:65]
	v_mfma_f32_16x16x32_bf16 v[58:61], v[138:141], v[146:149], v[58:61]
	v_mfma_f32_16x16x32_bf16 v[46:49], v[130:133], v[154:157], v[46:49]
	v_mfma_f32_16x16x32_bf16 v[42:45], v[138:141], v[154:157], v[42:45]
	v_mfma_f32_16x16x32_bf16 v[30:33], v[130:133], v[162:165], v[30:33]
	v_mfma_f32_16x16x32_bf16 v[26:29], v[138:141], v[162:165], v[26:29]
	v_mfma_f32_16x16x32_bf16 v[14:17], v[130:133], v[170:173], v[14:17]
	v_mfma_f32_16x16x32_bf16 v[10:13], v[138:141], v[170:173], v[10:13]
	v_mfma_f32_16x16x32_bf16 v[62:65], v[134:137], v[150:153], v[62:65]
	v_mfma_f32_16x16x32_bf16 v[58:61], v[142:145], v[150:153], v[58:61]
	v_mfma_f32_16x16x32_bf16 v[46:49], v[134:137], v[158:161], v[46:49]
	v_mfma_f32_16x16x32_bf16 v[42:45], v[142:145], v[158:161], v[42:45]
	v_mfma_f32_16x16x32_bf16 v[30:33], v[134:137], v[166:169], v[30:33]
	v_mfma_f32_16x16x32_bf16 v[26:29], v[142:145], v[166:169], v[26:29]
	v_mfma_f32_16x16x32_bf16 v[14:17], v[134:137], v[174:177], v[14:17]
	v_mfma_f32_16x16x32_bf16 v[10:13], v[142:145], v[174:177], v[10:13]
	s_barrier
	s_add_u32 s88, s90, 0x40000
	s_addc_u32 s89, s91, 0
	s_add_i32 s79, s87, s38
	s_mov_b32 m0, s79
	s_nop 0
	global_load_lds_dwordx4 v0, s[88:89]
	s_add_i32 m0, s79, 0x2000
	s_nop 0
	global_load_lds_dwordx4 v194, s[88:89]
	s_add_i32 s79, 0, 0x18000
	v_add_u32_e32 v142, s79, v212
	ds_read_b128 v[130:133], v142
	ds_read_b128 v[134:137], v142 offset:1024
	ds_read_b128 v[138:141], v142 offset:2048
	ds_read_b128 v[142:145], v142 offset:3072
	s_waitcnt vmcnt(6)
	s_barrier
	v_mfma_f32_16x16x32_bf16 v[54:57], v[178:181], v[146:149], v[54:57]
	v_mfma_f32_16x16x32_bf16 v[50:53], v[200:203], v[146:149], v[50:53]
	v_mfma_f32_16x16x32_bf16 v[38:41], v[178:181], v[154:157], v[38:41]
	v_mfma_f32_16x16x32_bf16 v[34:37], v[200:203], v[154:157], v[34:37]
	v_mfma_f32_16x16x32_bf16 v[22:25], v[178:181], v[162:165], v[22:25]
	v_mfma_f32_16x16x32_bf16 v[18:21], v[200:203], v[162:165], v[18:21]
	v_mfma_f32_16x16x32_bf16 v[6:9], v[178:181], v[170:173], v[6:9]
	v_mfma_f32_16x16x32_bf16 v[2:5], v[200:203], v[170:173], v[2:5]
	v_mfma_f32_16x16x32_bf16 v[54:57], v[182:185], v[150:153], v[54:57]
	v_mfma_f32_16x16x32_bf16 v[50:53], v[204:207], v[150:153], v[50:53]
	v_mfma_f32_16x16x32_bf16 v[38:41], v[182:185], v[158:161], v[38:41]
	v_mfma_f32_16x16x32_bf16 v[34:37], v[204:207], v[158:161], v[34:37]
	v_mfma_f32_16x16x32_bf16 v[22:25], v[182:185], v[166:169], v[22:25]
	v_mfma_f32_16x16x32_bf16 v[18:21], v[204:207], v[166:169], v[18:21]
	v_mfma_f32_16x16x32_bf16 v[6:9], v[182:185], v[174:177], v[6:9]
	v_mfma_f32_16x16x32_bf16 v[2:5], v[204:207], v[174:177], v[2:5]
	s_barrier
	s_add_u32 s88, s92, 0xc0000
	s_addc_u32 s89, s93, 0
	s_mov_b32 m0, s43
	ds_read_b128 v[146:149], v213 offset:32768
	ds_read_b128 v[150:153], v213 offset:33792
	ds_read_b128 v[154:157], v213 offset:34816
	ds_read_b128 v[158:161], v213 offset:35840
	ds_read_b128 v[162:165], v213 offset:36864
	ds_read_b128 v[166:169], v213 offset:37888
	ds_read_b128 v[170:173], v213 offset:38912
	ds_read_b128 v[174:177], v213 offset:39936
	global_load_lds_dwordx4 v190, s[88:89]
	s_mov_b32 m0, s44
	s_nop 0
	global_load_lds_dwordx4 v192, s[88:89]
	s_waitcnt lgkmcnt(8)
	s_barrier
	s_waitcnt lgkmcnt(0)
	v_mfma_f32_16x16x32_bf16 v[126:129], v[130:133], v[146:149], v[126:129]
	v_mfma_f32_16x16x32_bf16 v[122:125], v[138:141], v[146:149], v[122:125]
	v_mfma_f32_16x16x32_bf16 v[110:113], v[130:133], v[154:157], v[110:113]
	v_mfma_f32_16x16x32_bf16 v[106:109], v[138:141], v[154:157], v[106:109]
	v_mfma_f32_16x16x32_bf16 v[94:97], v[130:133], v[162:165], v[94:97]
	v_mfma_f32_16x16x32_bf16 v[90:93], v[138:141], v[162:165], v[90:93]
	v_mfma_f32_16x16x32_bf16 v[78:81], v[130:133], v[170:173], v[78:81]
	v_mfma_f32_16x16x32_bf16 v[74:77], v[138:141], v[170:173], v[74:77]
	v_mfma_f32_16x16x32_bf16 v[126:129], v[134:137], v[150:153], v[126:129]
	v_mfma_f32_16x16x32_bf16 v[122:125], v[142:145], v[150:153], v[122:125]
	v_mfma_f32_16x16x32_bf16 v[110:113], v[134:137], v[158:161], v[110:113]
	v_mfma_f32_16x16x32_bf16 v[106:109], v[142:145], v[158:161], v[106:109]
	v_mfma_f32_16x16x32_bf16 v[94:97], v[134:137], v[166:169], v[94:97]
	v_mfma_f32_16x16x32_bf16 v[90:93], v[142:145], v[166:169], v[90:93]
	v_mfma_f32_16x16x32_bf16 v[78:81], v[134:137], v[174:177], v[78:81]
	v_mfma_f32_16x16x32_bf16 v[74:77], v[142:145], v[174:177], v[74:77]
	s_barrier
	s_add_i32 s87, 0, 0x1c000
	s_add_i32 s79, s79, s38
	v_add_u32_e32 v204, s87, v212
	s_mov_b32 m0, s79
	ds_read_b128 v[178:181], v204
	ds_read_b128 v[182:185], v204 offset:1024
	ds_read_b128 v[200:203], v204 offset:2048
	ds_read_b128 v[204:207], v204 offset:3072
	s_add_u32 s98, s90, s40
	s_addc_u32 s99, s91, s41
	global_load_lds_dwordx4 v0, s[98:99]
	s_add_i32 m0, s79, 0x2000
	s_add_u32 s98, s90, s40
	s_addc_u32 s99, s91, s41
	global_load_lds_dwordx4 v194, s[98:99]
	s_barrier
	s_waitcnt lgkmcnt(0)
	v_mfma_f32_16x16x32_bf16 v[118:121], v[178:181], v[146:149], v[118:121]
	v_mfma_f32_16x16x32_bf16 v[114:117], v[200:203], v[146:149], v[114:117]
	v_mfma_f32_16x16x32_bf16 v[102:105], v[178:181], v[154:157], v[102:105]
	v_mfma_f32_16x16x32_bf16 v[98:101], v[200:203], v[154:157], v[98:101]
	v_mfma_f32_16x16x32_bf16 v[86:89], v[178:181], v[162:165], v[86:89]
	v_mfma_f32_16x16x32_bf16 v[82:85], v[200:203], v[162:165], v[82:85]
	v_mfma_f32_16x16x32_bf16 v[70:73], v[178:181], v[170:173], v[70:73]
	v_mfma_f32_16x16x32_bf16 v[66:69], v[200:203], v[170:173], v[66:69]
	v_mfma_f32_16x16x32_bf16 v[118:121], v[182:185], v[150:153], v[118:121]
	v_mfma_f32_16x16x32_bf16 v[114:117], v[204:207], v[150:153], v[114:117]
	v_mfma_f32_16x16x32_bf16 v[102:105], v[182:185], v[158:161], v[102:105]
	v_mfma_f32_16x16x32_bf16 v[98:101], v[204:207], v[158:161], v[98:101]
	v_mfma_f32_16x16x32_bf16 v[86:89], v[182:185], v[166:169], v[86:89]
	v_mfma_f32_16x16x32_bf16 v[82:85], v[204:207], v[166:169], v[82:85]
	v_mfma_f32_16x16x32_bf16 v[70:73], v[182:185], v[174:177], v[70:73]
	v_mfma_f32_16x16x32_bf16 v[66:69], v[204:207], v[174:177], v[66:69]
	s_mov_b32 m0, s60
	s_barrier
	ds_read_b128 v[146:149], v213 offset:49152
	ds_read_b128 v[150:153], v213 offset:50176
	ds_read_b128 v[154:157], v213 offset:51200
	ds_read_b128 v[158:161], v213 offset:52224
	ds_read_b128 v[162:165], v213 offset:53248
	ds_read_b128 v[166:169], v213 offset:54272
	ds_read_b128 v[170:173], v213 offset:55296
	ds_read_b128 v[174:177], v213 offset:56320
	s_add_u32 s98, s92, s40
	s_addc_u32 s99, s93, s41
	global_load_lds_dwordx4 v190, s[98:99]
	s_mov_b32 m0, s61
	s_add_u32 s98, s92, s40
	s_addc_u32 s99, s93, s41
	global_load_lds_dwordx4 v192, s[98:99]
	s_waitcnt vmcnt(10)
	s_barrier
	s_waitcnt lgkmcnt(0)
	v_mfma_f32_16x16x32_bf16 v[62:65], v[130:133], v[146:149], v[62:65]
	v_mfma_f32_16x16x32_bf16 v[58:61], v[138:141], v[146:149], v[58:61]
	v_mfma_f32_16x16x32_bf16 v[46:49], v[130:133], v[154:157], v[46:49]
	v_mfma_f32_16x16x32_bf16 v[42:45], v[138:141], v[154:157], v[42:45]
	v_mfma_f32_16x16x32_bf16 v[30:33], v[130:133], v[162:165], v[30:33]
	v_mfma_f32_16x16x32_bf16 v[26:29], v[138:141], v[162:165], v[26:29]
	v_mfma_f32_16x16x32_bf16 v[14:17], v[130:133], v[170:173], v[14:17]
	v_mfma_f32_16x16x32_bf16 v[10:13], v[138:141], v[170:173], v[10:13]
	v_mfma_f32_16x16x32_bf16 v[62:65], v[134:137], v[150:153], v[62:65]
	v_mfma_f32_16x16x32_bf16 v[58:61], v[142:145], v[150:153], v[58:61]
	v_mfma_f32_16x16x32_bf16 v[46:49], v[134:137], v[158:161], v[46:49]
	v_mfma_f32_16x16x32_bf16 v[42:45], v[142:145], v[158:161], v[42:45]
	v_mfma_f32_16x16x32_bf16 v[30:33], v[134:137], v[166:169], v[30:33]
	v_mfma_f32_16x16x32_bf16 v[26:29], v[142:145], v[166:169], v[26:29]
	v_mfma_f32_16x16x32_bf16 v[14:17], v[134:137], v[174:177], v[14:17]
	v_mfma_f32_16x16x32_bf16 v[10:13], v[142:145], v[174:177], v[10:13]
	s_barrier
	s_add_u32 s88, s90, 0x40080
	s_addc_u32 s89, s91, 0
	s_add_i32 s79, s87, s38
	s_mov_b32 m0, s79
	s_nop 0
	global_load_lds_dwordx4 v0, s[88:89]
	s_add_i32 m0, s79, 0x2000
	s_nop 0
	global_load_lds_dwordx4 v194, s[88:89]
	s_add_i32 s79, 0, 0x10000
	ds_read_b128 v[130:133], v189
	ds_read_b128 v[134:137], v189 offset:1024
	ds_read_b128 v[138:141], v189 offset:2048
	ds_read_b128 v[142:145], v189 offset:3072
	s_waitcnt vmcnt(6)
	s_barrier
	v_mfma_f32_16x16x32_bf16 v[54:57], v[178:181], v[146:149], v[54:57]
	v_mfma_f32_16x16x32_bf16 v[50:53], v[200:203], v[146:149], v[50:53]
	v_mfma_f32_16x16x32_bf16 v[38:41], v[178:181], v[154:157], v[38:41]
	v_mfma_f32_16x16x32_bf16 v[34:37], v[200:203], v[154:157], v[34:37]
	v_mfma_f32_16x16x32_bf16 v[22:25], v[178:181], v[162:165], v[22:25]
	v_mfma_f32_16x16x32_bf16 v[18:21], v[200:203], v[162:165], v[18:21]
	v_mfma_f32_16x16x32_bf16 v[6:9], v[178:181], v[170:173], v[6:9]
	v_mfma_f32_16x16x32_bf16 v[2:5], v[200:203], v[170:173], v[2:5]
	v_mfma_f32_16x16x32_bf16 v[54:57], v[182:185], v[150:153], v[54:57]
	v_mfma_f32_16x16x32_bf16 v[50:53], v[204:207], v[150:153], v[50:53]
	v_mfma_f32_16x16x32_bf16 v[38:41], v[182:185], v[158:161], v[38:41]
	v_mfma_f32_16x16x32_bf16 v[34:37], v[204:207], v[158:161], v[34:37]
	v_mfma_f32_16x16x32_bf16 v[22:25], v[182:185], v[166:169], v[22:25]
	v_mfma_f32_16x16x32_bf16 v[18:21], v[204:207], v[166:169], v[18:21]
	v_mfma_f32_16x16x32_bf16 v[6:9], v[182:185], v[174:177], v[6:9]
	v_mfma_f32_16x16x32_bf16 v[2:5], v[204:207], v[174:177], v[2:5]
	s_add_i32 s78, s78, 2
	s_add_u32 s34, s34, 0x100
	s_addc_u32 s75, s75, 0
	s_mov_b64 s[88:89], s[4:5]
	s_add_u32 s4, s88, 0x100
	s_addc_u32 s5, s89, 0
	s_cmp_eq_u32 s78, 12
	s_cselect_b32 s93, s17, s5
	s_cselect_b32 s92, s16, s4
	s_cselect_b32 s91, s15, s75
	s_cselect_b32 s90, s23, s34
	s_cmp_gt_u32 s78, 13
	s_barrier
	s_cbranch_scc0 .LBB0_838
	s_waitcnt lgkmcnt(0)
	s_lshl_b32 s4, s22, 8
	v_mov_b32_e32 v186, v252
	s_add_i32 s4, s4, s47
	s_nop 0
	v_and_or_b32 v202, v186, 15, s4
	s_lshl_b32 s4, s86, 8
	s_or_b32 s4, s4, s55
	v_lshrrev_b32_e32 v130, 1, v186
	v_and_or_b32 v200, v130, 24, s4
	v_ashrrev_i32_e32 v201, 31, v200
	v_ashrrev_i32_e32 v203, 31, v202
	v_lshl_add_u64 v[204:205], v[200:201], 2, s[6:7]
	v_lshlrev_b64 v[130:131], 12, v[202:203]
	v_lshl_add_u64 v[130:131], v[204:205], 0, v[130:131]
	global_load_dwordx4 v[216:219], v[130:131], off offset:16
	global_load_dwordx4 v[220:223], v[130:131], off
	global_load_dwordx4 v[178:181], v[130:131], off offset:528
	global_load_dwordx4 v[182:185], v[130:131], off offset:512
	v_or_b32_e32 v210, 16, v202
	v_ashrrev_i32_e32 v211, 31, v210
	v_lshlrev_b64 v[130:131], 12, v[210:211]
	v_or_b32_e32 v208, 32, v202
	v_lshl_add_u64 v[130:131], v[204:205], 0, v[130:131]
	v_ashrrev_i32_e32 v209, 31, v208
	global_load_dwordx4 v[170:173], v[130:131], off offset:16
	global_load_dwordx4 v[174:177], v[130:131], off
	global_load_dwordx4 v[162:165], v[130:131], off offset:528
	global_load_dwordx4 v[166:169], v[130:131], off offset:512
	v_lshlrev_b64 v[130:131], 12, v[208:209]
	v_or_b32_e32 v206, 48, v202
	v_lshl_add_u64 v[130:131], v[204:205], 0, v[130:131]
	v_ashrrev_i32_e32 v207, 31, v206
	global_load_dwordx4 v[154:157], v[130:131], off offset:16
	global_load_dwordx4 v[158:161], v[130:131], off
	global_load_dwordx4 v[138:141], v[130:131], off offset:528
	global_load_dwordx4 v[142:145], v[130:131], off offset:512
	v_lshlrev_b64 v[130:131], 12, v[206:207]
	v_lshl_add_u64 v[134:135], v[204:205], 0, v[130:131]
	global_load_dwordx4 v[146:149], v[134:135], off offset:16
	global_load_dwordx4 v[150:153], v[134:135], off
	global_load_dwordx4 v[130:133], v[134:135], off offset:528
	s_nop 0
	global_load_dwordx4 v[134:137], v[134:135], off offset:512
	v_and_b32_e32 v186, 63, v186
	v_lshlrev_b32_e32 v187, 2, v186
	v_xor_b32_e32 v215, 64, v187
	v_xor_b32_e32 v214, 0x80, v187
	v_cmp_gt_u32_e32 vcc, 16, v186
	v_lshlrev_b64 v[186:187], 10, v[202:203]
	v_lshl_add_u64 v[186:187], v[186:187], 0, v[200:201]
	s_lshl_b32 s4, s86, 2
	s_ashr_i32 s5, s4, 31
	s_waitcnt vmcnt(0)
	v_pk_add_f32 v[124:125], v[124:125], v[218:219]
	v_pk_add_f32 v[128:129], v[128:129], v[222:223]
	v_pk_add_f32 v[126:127], v[126:127], v[220:221]
	v_pk_mul_f32 v[218:219], v[128:129], v[128:129]
	v_pk_mul_f32 v[220:221], v[126:127], v[126:127]
	v_pk_add_f32 v[122:123], v[122:123], v[216:217]
	v_lshl_add_u64 v[216:217], v[186:187], 2, s[12:13]
	v_add_f32_e32 v220, v220, v221
	v_add_f32_e32 v218, v218, v219
	global_store_dwordx4 v[216:217], v[126:129], off
	global_store_dwordx4 v[216:217], v[122:125], off offset:16
	v_add_f32_e32 v222, v220, v218
	v_pk_mul_f32 v[220:221], v[122:123], v[122:123]
	v_cvt_pk_bf16_f32 v126, v126, v127
	v_cvt_pk_bf16_f32 v127, v128, v129
	v_cvt_pk_bf16_f32 v128, v122, v123
	v_cvt_pk_bf16_f32 v129, v124, v125
	v_lshl_add_u64 v[122:123], v[186:187], 1, s[8:9]
	v_pk_add_f32 v[120:121], v[120:121], v[184:185]
	v_pk_add_f32 v[118:119], v[118:119], v[182:183]
	v_pk_mul_f32 v[218:219], v[124:125], v[124:125]
	global_store_dwordx4 v[122:123], v[126:129], off
	v_pk_mul_f32 v[124:125], v[120:121], v[120:121]
	v_pk_add_f32 v[116:117], v[116:117], v[180:181]
	v_pk_mul_f32 v[126:127], v[118:119], v[118:119]
	v_pk_add_f32 v[114:115], v[114:115], v[178:179]
	v_add_f32_e32 v126, v126, v127
	v_add_f32_e32 v124, v124, v125
	v_add_f32_e32 v128, v126, v124
	v_pk_mul_f32 v[124:125], v[116:117], v[116:117]
	v_pk_mul_f32 v[126:127], v[114:115], v[114:115]
	v_add_f32_e32 v220, v220, v221
	v_add_f32_e32 v218, v218, v219
	v_add_f32_e32 v126, v126, v127
	v_add_f32_e32 v124, v124, v125
	v_add_f32_e32 v218, v220, v218
	v_add_f32_e32 v124, v126, v124
	v_add_f32_e32 v218, v222, v218
	v_add_f32_e32 v124, v128, v124
	v_add_f32_e32 v124, v218, v124
	global_store_dwordx4 v[216:217], v[118:121], off offset:512
	global_store_dwordx4 v[216:217], v[114:117], off offset:528
	s_nop 0
	v_cvt_pk_bf16_f32 v118, v118, v119
	v_cvt_pk_bf16_f32 v119, v120, v121
	v_cvt_pk_bf16_f32 v120, v114, v115
	ds_bpermute_b32 v114, v215, v124
	v_cvt_pk_bf16_f32 v121, v116, v117
	global_store_dwordx4 v[122:123], v[118:121], off offset:256
	s_waitcnt lgkmcnt(0)
	v_add_f32_e32 v114, v124, v114
	ds_bpermute_b32 v115, v214, v114
	s_and_saveexec_b64 s[22:23], vcc
	s_cbranch_execz .LBB0_841
	v_lshlrev_b64 v[116:117], 6, v[202:203]
	v_lshl_add_u64 v[116:117], s[10:11], 0, v[116:117]
	v_lshl_add_u64 v[116:117], s[4:5], 2, v[116:117]
	s_lshl_b32 s34, s45, 2
	v_lshl_add_u64 v[116:117], v[116:117], 0, s[34:35]
	s_waitcnt lgkmcnt(0)
	v_add_f32_e32 v114, v114, v115
	global_store_dword v[116:117], v114, off

.LBB0_918:
	s_ashr_i32 s17, s16, 31
	s_lshl_b64 s[22:23], s[16:17], 19
	v_mov_b64_e32 v[2:3], 0xb00
	s_add_u32 s84, s8, s22
	v_cmp_lt_i64_e32 vcc, s[28:29], v[2:3]
	s_addc_u32 s85, s9, s23
	s_and_b64 s[22:23], vcc, exec
	s_cselect_b32 s17, s85, s7
	s_cselect_b32 s22, s84, s6
	s_ashr_i32 s15, s14, 31
	s_lshl_b64 s[28:29], s[14:15], 19
	s_add_u32 s86, s37, s28
	s_addc_u32 s87, s38, s29
	s_and_b64 s[28:29], vcc, exec
	s_cselect_b32 s15, s87, s89
	s_cselect_b32 s23, s86, s88
	s_add_u32 s28, s88, 0x100
	v_mov_b32_e32 v70, 0
	s_addc_u32 s29, s89, 0
	s_mov_b32 s45, -2
	v_mov_b32_e32 v71, v70
	v_mov_b32_e32 v72, v70
	v_mov_b32_e32 v73, v70
	v_mov_b32_e32 v74, v70
	v_mov_b32_e32 v75, v70
	v_mov_b32_e32 v76, v70
	v_mov_b32_e32 v77, v70
	v_mov_b32_e32 v66, v70
	v_mov_b32_e32 v67, v70
	v_mov_b32_e32 v68, v70
	v_mov_b32_e32 v69, v70
	v_mov_b32_e32 v78, v70
	v_mov_b32_e32 v79, v70
	v_mov_b32_e32 v80, v70
	v_mov_b32_e32 v81, v70
	v_mov_b32_e32 v94, v70
	v_mov_b32_e32 v95, v70
	v_mov_b32_e32 v96, v70
	v_mov_b32_e32 v97, v70
	v_mov_b32_e32 v90, v70
	v_mov_b32_e32 v91, v70
	v_mov_b32_e32 v92, v70
	v_mov_b32_e32 v93, v70
	v_mov_b32_e32 v82, v70
	v_mov_b32_e32 v83, v70
	v_mov_b32_e32 v84, v70
	v_mov_b32_e32 v85, v70
	v_mov_b32_e32 v86, v70
	v_mov_b32_e32 v87, v70
	v_mov_b32_e32 v88, v70
	v_mov_b32_e32 v89, v70
	v_mov_b32_e32 v10, v70
	v_mov_b32_e32 v11, v70
	v_mov_b32_e32 v12, v70
	v_mov_b32_e32 v13, v70
	v_mov_b32_e32 v14, v70
	v_mov_b32_e32 v15, v70
	v_mov_b32_e32 v16, v70
	v_mov_b32_e32 v17, v70
	v_mov_b32_e32 v6, v70
	v_mov_b32_e32 v7, v70
	v_mov_b32_e32 v8, v70
	v_mov_b32_e32 v9, v70
	v_mov_b32_e32 v2, v70
	v_mov_b32_e32 v3, v70
	v_mov_b32_e32 v4, v70
	v_mov_b32_e32 v5, v70
	v_mov_b32_e32 v26, v70
	v_mov_b32_e32 v27, v70
	v_mov_b32_e32 v28, v70
	v_mov_b32_e32 v29, v70
	v_mov_b32_e32 v30, v70
	v_mov_b32_e32 v31, v70
	v_mov_b32_e32 v32, v70
	v_mov_b32_e32 v33, v70
	v_mov_b32_e32 v22, v70
	v_mov_b32_e32 v23, v70
	v_mov_b32_e32 v24, v70
	v_mov_b32_e32 v25, v70
	v_mov_b32_e32 v18, v70
	v_mov_b32_e32 v19, v70
	v_mov_b32_e32 v20, v70
	v_mov_b32_e32 v21, v70
	v_mov_b32_e32 v34, v70
	v_mov_b32_e32 v35, v70
	v_mov_b32_e32 v36, v70
	v_mov_b32_e32 v37, v70
	v_mov_b32_e32 v38, v70
	v_mov_b32_e32 v39, v70
	v_mov_b32_e32 v40, v70
	v_mov_b32_e32 v41, v70
	v_mov_b32_e32 v46, v70
	v_mov_b32_e32 v47, v70
	v_mov_b32_e32 v48, v70
	v_mov_b32_e32 v49, v70
	v_mov_b32_e32 v50, v70
	v_mov_b32_e32 v51, v70
	v_mov_b32_e32 v52, v70
	v_mov_b32_e32 v53, v70
	v_mov_b32_e32 v42, v70
	v_mov_b32_e32 v43, v70
	v_mov_b32_e32 v44, v70
	v_mov_b32_e32 v45, v70
	v_mov_b32_e32 v54, v70
	v_mov_b32_e32 v55, v70
	v_mov_b32_e32 v56, v70
	v_mov_b32_e32 v57, v70
	v_mov_b32_e32 v58, v70
	v_mov_b32_e32 v59, v70
	v_mov_b32_e32 v60, v70
	v_mov_b32_e32 v61, v70
	v_mov_b32_e32 v62, v70
	v_mov_b32_e32 v63, v70
	v_mov_b32_e32 v64, v70
	v_mov_b32_e32 v65, v70
	v_mov_b32_e32 v98, v70
	v_mov_b32_e32 v99, v70
	v_mov_b32_e32 v100, v70
	v_mov_b32_e32 v101, v70
	v_mov_b32_e32 v102, v70
	v_mov_b32_e32 v103, v70
	v_mov_b32_e32 v104, v70
	v_mov_b32_e32 v105, v70
	v_mov_b32_e32 v106, v70
	v_mov_b32_e32 v107, v70
	v_mov_b32_e32 v108, v70
	v_mov_b32_e32 v109, v70
	v_mov_b32_e32 v118, v70
	v_mov_b32_e32 v119, v70
	v_mov_b32_e32 v120, v70
	v_mov_b32_e32 v121, v70
	v_mov_b32_e32 v110, v70
	v_mov_b32_e32 v111, v70
	v_mov_b32_e32 v112, v70
	v_mov_b32_e32 v113, v70
	v_mov_b32_e32 v114, v70
	v_mov_b32_e32 v115, v70
	v_mov_b32_e32 v116, v70
	v_mov_b32_e32 v117, v70
	v_mov_b32_e32 v122, v70
	v_mov_b32_e32 v123, v70
	v_mov_b32_e32 v124, v70
	v_mov_b32_e32 v125, v70
	v_mov_b32_e32 v126, v70
	v_mov_b32_e32 v127, v70
	v_mov_b32_e32 v128, v70
	v_mov_b32_e32 v129, v70
	s_add_i32 vcc_lo, 0, 0x10000
	v_add_u32_e32 v0, vcc_lo, v254
	v_add_u32_e32 v189, 0x10000, v254
	ds_read_b128 v[130:133], v0
	ds_read_b128 v[134:137], v0 offset:1024
	ds_read_b128 v[138:141], v0 offset:2048
	ds_read_b128 v[142:145], v0 offset:3072
	s_add_u32 s88, s6, 0x100
	s_addc_u32 s89, s7, 0
	s_cmp_eq_u32 s45, 12
	s_cselect_b32 s93, s17, s89
	s_cselect_b32 s92, s22, s88
	s_cselect_b32 s91, s15, s29
	s_cselect_b32 s90, s23, s28
.LBB0_919:
	s_add_i32 m0, s43, 0xc000
	ds_read_b128 v[146:149], v253
	ds_read_b128 v[150:153], v253 offset:1024
	ds_read_b128 v[168:171], v253 offset:2048
	ds_read_b128 v[172:175], v253 offset:3072
	ds_read_b128 v[176:179], v253 offset:4096
	ds_read_b128 v[180:183], v253 offset:5120
	ds_read_b128 v[184:187], v253 offset:6144
	ds_read_b128 v[190:193], v253 offset:7168
	global_load_lds_dwordx4 v164, s[6:7]
	s_add_i32 m0, s43, 0xe000
	v_lshl_add_u64 v[154:155], s[6:7], 0, v[166:167]
	global_load_lds_dwordx4 v[154:155], off
	s_waitcnt lgkmcnt(8)
	s_barrier
	s_waitcnt lgkmcnt(0)
	v_mfma_f32_16x16x32_bf16 v[126:129], v[130:133], v[146:149], v[126:129]
	v_mfma_f32_16x16x32_bf16 v[70:73], v[138:141], v[146:149], v[70:73]
	v_mfma_f32_16x16x32_bf16 v[122:125], v[130:133], v[168:171], v[122:125]
	v_mfma_f32_16x16x32_bf16 v[74:77], v[138:141], v[168:171], v[74:77]
	v_mfma_f32_16x16x32_bf16 v[114:117], v[130:133], v[176:179], v[114:117]
	v_mfma_f32_16x16x32_bf16 v[66:69], v[138:141], v[176:179], v[66:69]
	v_mfma_f32_16x16x32_bf16 v[110:113], v[130:133], v[184:187], v[110:113]
	v_mfma_f32_16x16x32_bf16 v[78:81], v[138:141], v[184:187], v[78:81]
	v_mfma_f32_16x16x32_bf16 v[126:129], v[134:137], v[150:153], v[126:129]
	v_mfma_f32_16x16x32_bf16 v[70:73], v[142:145], v[150:153], v[70:73]
	v_mfma_f32_16x16x32_bf16 v[122:125], v[134:137], v[172:175], v[122:125]
	v_mfma_f32_16x16x32_bf16 v[74:77], v[142:145], v[172:175], v[74:77]
	v_mfma_f32_16x16x32_bf16 v[114:117], v[134:137], v[180:183], v[114:117]
	v_mfma_f32_16x16x32_bf16 v[66:69], v[142:145], v[180:183], v[66:69]
	v_mfma_f32_16x16x32_bf16 v[110:113], v[134:137], v[190:193], v[110:113]
	v_mfma_f32_16x16x32_bf16 v[78:81], v[142:145], v[190:193], v[78:81]
	s_barrier
	s_add_i32 vcc_hi, 0, 0x14000
	s_add_i32 s6, vcc_lo, s39
	s_mov_b32 m0, s6
	ds_read_b128 v[194:197], v189 offset:16384
	ds_read_b128 v[198:201], v189 offset:17408
	ds_read_b128 v[202:205], v189 offset:18432
	ds_read_b128 v[206:209], v189 offset:19456
	global_load_lds_dwordx4 v160, s[90:91]
	s_add_i32 m0, s6, 0x2000
	s_nop 0
	global_load_lds_dwordx4 v156, s[90:91]
	s_barrier
	s_waitcnt lgkmcnt(0)
	v_mfma_f32_16x16x32_bf16 v[118:121], v[194:197], v[146:149], v[118:121]
	v_mfma_f32_16x16x32_bf16 v[94:97], v[202:205], v[146:149], v[94:97]
	v_mfma_f32_16x16x32_bf16 v[106:109], v[194:197], v[168:171], v[106:109]
	v_mfma_f32_16x16x32_bf16 v[90:93], v[202:205], v[168:171], v[90:93]
	v_mfma_f32_16x16x32_bf16 v[102:105], v[194:197], v[176:179], v[102:105]
	v_mfma_f32_16x16x32_bf16 v[82:85], v[202:205], v[176:179], v[82:85]
	v_mfma_f32_16x16x32_bf16 v[98:101], v[194:197], v[184:187], v[98:101]
	v_mfma_f32_16x16x32_bf16 v[86:89], v[202:205], v[184:187], v[86:89]
	v_mfma_f32_16x16x32_bf16 v[118:121], v[198:201], v[150:153], v[118:121]
	v_mfma_f32_16x16x32_bf16 v[94:97], v[206:209], v[150:153], v[94:97]
	v_mfma_f32_16x16x32_bf16 v[106:109], v[198:201], v[172:175], v[106:109]
	v_mfma_f32_16x16x32_bf16 v[90:93], v[206:209], v[172:175], v[90:93]
	v_mfma_f32_16x16x32_bf16 v[102:105], v[198:201], v[180:183], v[102:105]
	v_mfma_f32_16x16x32_bf16 v[82:85], v[206:209], v[180:183], v[82:85]
	v_mfma_f32_16x16x32_bf16 v[98:101], v[198:201], v[190:193], v[98:101]
	v_mfma_f32_16x16x32_bf16 v[86:89], v[206:209], v[190:193], v[86:89]
	s_mov_b32 m0, s43
	s_mov_b64 s[100:101], s[92:93]
	s_barrier
	ds_read_b128 v[146:149], v253 offset:16384
	ds_read_b128 v[150:153], v253 offset:17408
	ds_read_b128 v[168:171], v253 offset:18432
	ds_read_b128 v[172:175], v253 offset:19456
	ds_read_b128 v[176:179], v253 offset:20480
	ds_read_b128 v[180:183], v253 offset:21504
	ds_read_b128 v[184:187], v253 offset:22528
	ds_read_b128 v[190:193], v253 offset:23552
	global_load_lds_dwordx4 v162, s[100:101]
	s_mov_b32 m0, s60
	s_nop 0
	global_load_lds_dwordx4 v158, s[100:101]
	s_waitcnt vmcnt(10)
	s_barrier
	s_waitcnt lgkmcnt(0)
	v_mfma_f32_16x16x32_bf16 v[62:65], v[130:133], v[146:149], v[62:65]
	v_mfma_f32_16x16x32_bf16 v[10:13], v[138:141], v[146:149], v[10:13]
	v_mfma_f32_16x16x32_bf16 v[58:61], v[130:133], v[168:171], v[58:61]
	v_mfma_f32_16x16x32_bf16 v[14:17], v[138:141], v[168:171], v[14:17]
	v_mfma_f32_16x16x32_bf16 v[54:57], v[130:133], v[176:179], v[54:57]
	v_mfma_f32_16x16x32_bf16 v[6:9], v[138:141], v[176:179], v[6:9]
	v_mfma_f32_16x16x32_bf16 v[42:45], v[130:133], v[184:187], v[42:45]
	v_mfma_f32_16x16x32_bf16 v[2:5], v[138:141], v[184:187], v[2:5]
	v_mfma_f32_16x16x32_bf16 v[62:65], v[134:137], v[150:153], v[62:65]
	v_mfma_f32_16x16x32_bf16 v[10:13], v[142:145], v[150:153], v[10:13]
	v_mfma_f32_16x16x32_bf16 v[58:61], v[134:137], v[172:175], v[58:61]
	v_mfma_f32_16x16x32_bf16 v[14:17], v[142:145], v[172:175], v[14:17]
	v_mfma_f32_16x16x32_bf16 v[54:57], v[134:137], v[180:183], v[54:57]
	v_mfma_f32_16x16x32_bf16 v[6:9], v[142:145], v[180:183], v[6:9]
	v_mfma_f32_16x16x32_bf16 v[42:45], v[134:137], v[190:193], v[42:45]
	v_mfma_f32_16x16x32_bf16 v[2:5], v[142:145], v[190:193], v[2:5]
	s_barrier
	s_add_u32 s6, s90, 0x40000
	s_addc_u32 s7, s91, 0
	s_add_i32 vcc_lo, vcc_hi, s39
	s_mov_b32 m0, vcc_lo
	s_nop 0
	global_load_lds_dwordx4 v160, s[6:7]
	s_add_i32 m0, vcc_lo, 0x2000
	s_nop 0
	global_load_lds_dwordx4 v156, s[6:7]
	s_add_i32 vcc_lo, 0, 0x18000
	ds_read_b128 v[130:133], v189 offset:32768
	ds_read_b128 v[134:137], v189 offset:33792
	ds_read_b128 v[138:141], v189 offset:34816
	ds_read_b128 v[142:145], v189 offset:35840
	s_waitcnt vmcnt(6)
	s_barrier
	v_mfma_f32_16x16x32_bf16 v[50:53], v[194:197], v[146:149], v[50:53]
	v_mfma_f32_16x16x32_bf16 v[26:29], v[202:205], v[146:149], v[26:29]
	v_mfma_f32_16x16x32_bf16 v[46:49], v[194:197], v[168:171], v[46:49]
	v_mfma_f32_16x16x32_bf16 v[30:33], v[202:205], v[168:171], v[30:33]
	v_mfma_f32_16x16x32_bf16 v[38:41], v[194:197], v[176:179], v[38:41]
	v_mfma_f32_16x16x32_bf16 v[22:25], v[202:205], v[176:179], v[22:25]
	v_mfma_f32_16x16x32_bf16 v[34:37], v[194:197], v[184:187], v[34:37]
	v_mfma_f32_16x16x32_bf16 v[18:21], v[202:205], v[184:187], v[18:21]
	v_mfma_f32_16x16x32_bf16 v[50:53], v[198:201], v[150:153], v[50:53]
	v_mfma_f32_16x16x32_bf16 v[26:29], v[206:209], v[150:153], v[26:29]
	v_mfma_f32_16x16x32_bf16 v[46:49], v[198:201], v[172:175], v[46:49]
	v_mfma_f32_16x16x32_bf16 v[30:33], v[206:209], v[172:175], v[30:33]
	v_mfma_f32_16x16x32_bf16 v[38:41], v[198:201], v[180:183], v[38:41]
	v_mfma_f32_16x16x32_bf16 v[22:25], v[206:209], v[180:183], v[22:25]
	v_mfma_f32_16x16x32_bf16 v[34:37], v[198:201], v[190:193], v[34:37]
	v_mfma_f32_16x16x32_bf16 v[18:21], v[206:209], v[190:193], v[18:21]
	s_barrier
	s_add_u32 s6, s92, 0x40000
	s_addc_u32 s7, s93, 0
	s_mov_b32 m0, s61
	ds_read_b128 v[146:149], v253 offset:32768
	ds_read_b128 v[150:153], v253 offset:33792
	ds_read_b128 v[168:171], v253 offset:34816
	ds_read_b128 v[172:175], v253 offset:35840
	ds_read_b128 v[176:179], v253 offset:36864
	ds_read_b128 v[180:183], v253 offset:37888
	ds_read_b128 v[184:187], v253 offset:38912
	ds_read_b128 v[190:193], v253 offset:39936
	global_load_lds_dwordx4 v162, s[6:7]
	s_mov_b32 m0, s72
	s_nop 0
	global_load_lds_dwordx4 v158, s[6:7]
	s_waitcnt lgkmcnt(8)
	s_barrier
	s_waitcnt lgkmcnt(0)
	v_mfma_f32_16x16x32_bf16 v[126:129], v[130:133], v[146:149], v[126:129]
	v_mfma_f32_16x16x32_bf16 v[70:73], v[138:141], v[146:149], v[70:73]
	v_mfma_f32_16x16x32_bf16 v[122:125], v[130:133], v[168:171], v[122:125]
	v_mfma_f32_16x16x32_bf16 v[74:77], v[138:141], v[168:171], v[74:77]
	v_mfma_f32_16x16x32_bf16 v[114:117], v[130:133], v[176:179], v[114:117]
	v_mfma_f32_16x16x32_bf16 v[66:69], v[138:141], v[176:179], v[66:69]
	v_mfma_f32_16x16x32_bf16 v[110:113], v[130:133], v[184:187], v[110:113]
	v_mfma_f32_16x16x32_bf16 v[78:81], v[138:141], v[184:187], v[78:81]
	v_mfma_f32_16x16x32_bf16 v[126:129], v[134:137], v[150:153], v[126:129]
	v_mfma_f32_16x16x32_bf16 v[70:73], v[142:145], v[150:153], v[70:73]
	v_mfma_f32_16x16x32_bf16 v[122:125], v[134:137], v[172:175], v[122:125]
	v_mfma_f32_16x16x32_bf16 v[74:77], v[142:145], v[172:175], v[74:77]
	v_mfma_f32_16x16x32_bf16 v[114:117], v[134:137], v[180:183], v[114:117]
	v_mfma_f32_16x16x32_bf16 v[66:69], v[142:145], v[180:183], v[66:69]
	v_mfma_f32_16x16x32_bf16 v[110:113], v[134:137], v[190:193], v[110:113]
	v_mfma_f32_16x16x32_bf16 v[78:81], v[142:145], v[190:193], v[78:81]
	s_barrier
	s_add_i32 s92, 0, 0x1c000
	s_add_i32 s6, vcc_lo, s39
	s_mov_b32 m0, s6
	ds_read_b128 v[194:197], v189 offset:49152
	ds_read_b128 v[198:201], v189 offset:50176
	ds_read_b128 v[202:205], v189 offset:51200
	ds_read_b128 v[206:209], v189 offset:52224
	s_add_u32 s98, s90, s40
	s_addc_u32 s99, s91, s41
	global_load_lds_dwordx4 v160, s[98:99]
	s_add_i32 m0, s6, 0x2000
	s_add_u32 s98, s90, s40
	s_addc_u32 s99, s91, s41
	global_load_lds_dwordx4 v156, s[98:99]
	s_barrier
	s_waitcnt lgkmcnt(0)
	v_mfma_f32_16x16x32_bf16 v[118:121], v[194:197], v[146:149], v[118:121]
	v_mfma_f32_16x16x32_bf16 v[94:97], v[202:205], v[146:149], v[94:97]
	v_mfma_f32_16x16x32_bf16 v[106:109], v[194:197], v[168:171], v[106:109]
	v_mfma_f32_16x16x32_bf16 v[90:93], v[202:205], v[168:171], v[90:93]
	v_mfma_f32_16x16x32_bf16 v[102:105], v[194:197], v[176:179], v[102:105]
	v_mfma_f32_16x16x32_bf16 v[82:85], v[202:205], v[176:179], v[82:85]
	v_mfma_f32_16x16x32_bf16 v[98:101], v[194:197], v[184:187], v[98:101]
	v_mfma_f32_16x16x32_bf16 v[86:89], v[202:205], v[184:187], v[86:89]
	v_mfma_f32_16x16x32_bf16 v[118:121], v[198:201], v[150:153], v[118:121]
	v_mfma_f32_16x16x32_bf16 v[94:97], v[206:209], v[150:153], v[94:97]
	v_mfma_f32_16x16x32_bf16 v[106:109], v[198:201], v[172:175], v[106:109]
	v_mfma_f32_16x16x32_bf16 v[90:93], v[206:209], v[172:175], v[90:93]
	v_mfma_f32_16x16x32_bf16 v[102:105], v[198:201], v[180:183], v[102:105]
	v_mfma_f32_16x16x32_bf16 v[82:85], v[206:209], v[180:183], v[82:85]
	v_mfma_f32_16x16x32_bf16 v[98:101], v[198:201], v[190:193], v[98:101]
	v_mfma_f32_16x16x32_bf16 v[86:89], v[206:209], v[190:193], v[86:89]
	s_mov_b32 m0, s95
	s_barrier
	ds_read_b128 v[146:149], v253 offset:49152
	ds_read_b128 v[150:153], v253 offset:50176
	ds_read_b128 v[168:171], v253 offset:51200
	ds_read_b128 v[172:175], v253 offset:52224
	ds_read_b128 v[176:179], v253 offset:53248
	ds_read_b128 v[180:183], v253 offset:54272
	ds_read_b128 v[184:187], v253 offset:55296
	ds_read_b128 v[190:193], v253 offset:56320
	s_add_u32 s98, s100, s40
	s_addc_u32 s99, s101, s41
	global_load_lds_dwordx4 v162, s[98:99]
	s_mov_b32 m0, s96
	s_add_u32 s98, s100, s40
	s_addc_u32 s99, s101, s41
	global_load_lds_dwordx4 v158, s[98:99]
	s_waitcnt vmcnt(10)
	s_barrier
	s_waitcnt lgkmcnt(0)
	v_mfma_f32_16x16x32_bf16 v[62:65], v[130:133], v[146:149], v[62:65]
	v_mfma_f32_16x16x32_bf16 v[10:13], v[138:141], v[146:149], v[10:13]
	v_mfma_f32_16x16x32_bf16 v[58:61], v[130:133], v[168:171], v[58:61]
	v_mfma_f32_16x16x32_bf16 v[14:17], v[138:141], v[168:171], v[14:17]
	v_mfma_f32_16x16x32_bf16 v[54:57], v[130:133], v[176:179], v[54:57]
	v_mfma_f32_16x16x32_bf16 v[6:9], v[138:141], v[176:179], v[6:9]
	v_mfma_f32_16x16x32_bf16 v[42:45], v[130:133], v[184:187], v[42:45]
	v_mfma_f32_16x16x32_bf16 v[2:5], v[138:141], v[184:187], v[2:5]
	v_mfma_f32_16x16x32_bf16 v[62:65], v[134:137], v[150:153], v[62:65]
	v_mfma_f32_16x16x32_bf16 v[10:13], v[142:145], v[150:153], v[10:13]
	v_mfma_f32_16x16x32_bf16 v[58:61], v[134:137], v[172:175], v[58:61]
	v_mfma_f32_16x16x32_bf16 v[14:17], v[142:145], v[172:175], v[14:17]
	v_mfma_f32_16x16x32_bf16 v[54:57], v[134:137], v[180:183], v[54:57]
	v_mfma_f32_16x16x32_bf16 v[6:9], v[142:145], v[180:183], v[6:9]
	v_mfma_f32_16x16x32_bf16 v[42:45], v[134:137], v[190:193], v[42:45]
	v_mfma_f32_16x16x32_bf16 v[2:5], v[142:145], v[190:193], v[2:5]
	s_barrier
	s_add_u32 s6, s90, 0x40080
	s_addc_u32 s7, s91, 0
	s_add_i32 s90, s92, s39
	s_mov_b32 m0, s90
	s_nop 0
	global_load_lds_dwordx4 v160, s[6:7]
	s_add_i32 m0, s90, 0x2000
	s_nop 0
	global_load_lds_dwordx4 v156, s[6:7]
	s_add_i32 vcc_lo, 0, 0x10000
	ds_read_b128 v[130:133], v189
	ds_read_b128 v[134:137], v189 offset:1024
	ds_read_b128 v[138:141], v189 offset:2048
	ds_read_b128 v[142:145], v189 offset:3072
	s_waitcnt vmcnt(6)
	s_barrier
	v_mfma_f32_16x16x32_bf16 v[50:53], v[194:197], v[146:149], v[50:53]
	v_mfma_f32_16x16x32_bf16 v[26:29], v[202:205], v[146:149], v[26:29]
	v_mfma_f32_16x16x32_bf16 v[46:49], v[194:197], v[168:171], v[46:49]
	v_mfma_f32_16x16x32_bf16 v[30:33], v[202:205], v[168:171], v[30:33]
	v_mfma_f32_16x16x32_bf16 v[38:41], v[194:197], v[176:179], v[38:41]
	v_mfma_f32_16x16x32_bf16 v[22:25], v[202:205], v[176:179], v[22:25]
	v_mfma_f32_16x16x32_bf16 v[34:37], v[194:197], v[184:187], v[34:37]
	v_mfma_f32_16x16x32_bf16 v[18:21], v[202:205], v[184:187], v[18:21]
	v_mfma_f32_16x16x32_bf16 v[50:53], v[198:201], v[150:153], v[50:53]
	v_mfma_f32_16x16x32_bf16 v[26:29], v[206:209], v[150:153], v[26:29]
	v_mfma_f32_16x16x32_bf16 v[46:49], v[198:201], v[172:175], v[46:49]
	v_mfma_f32_16x16x32_bf16 v[30:33], v[206:209], v[172:175], v[30:33]
	v_mfma_f32_16x16x32_bf16 v[38:41], v[198:201], v[180:183], v[38:41]
	v_mfma_f32_16x16x32_bf16 v[22:25], v[206:209], v[180:183], v[22:25]
	v_mfma_f32_16x16x32_bf16 v[34:37], v[198:201], v[190:193], v[34:37]
	v_mfma_f32_16x16x32_bf16 v[18:21], v[206:209], v[190:193], v[18:21]
	s_add_i32 s45, s45, 2
	s_add_u32 s28, s28, 0x100
	s_addc_u32 s29, s29, 0
	s_mov_b64 s[6:7], s[88:89]
	s_add_u32 s88, s6, 0x100
	s_addc_u32 s89, s7, 0
	s_cmp_eq_u32 s45, 12
	s_cselect_b32 s93, s17, s89
	s_cselect_b32 s92, s22, s88
	s_cselect_b32 s91, s15, s29
	s_cselect_b32 s90, s23, s28
	s_cmp_gt_u32 s45, 13
	s_barrier
	s_cbranch_scc0 .LBB0_919
	s_waitcnt lgkmcnt(0)
	v_mov_b32_e32 v131, v252
	s_lshl_b32 s88, s5, 7
	v_bfe_u32 v130, v131, 4, 2
	v_and_b32_e32 v134, 15, v131
	v_lshlrev_b32_e32 v0, 4, v130
	s_ashr_i32 s89, s88, 31
	s_lshl_b32 s15, s4, 8
	v_or3_b32 v135, v0, s97, v134
	s_lshl_b64 s[4:5], s[88:89], 2
	v_lshrrev_b32_e32 v140, 1, v135
	s_add_u32 s4, s73, s4
	s_addc_u32 s5, s74, s5
	v_lshlrev_b32_e32 v0, 2, v140
	v_and_b32_e32 v144, 1, v131
	v_lshl_add_u64 v[132:133], s[4:5], 0, v[0:1]
	v_cmp_eq_u32_e32 vcc, 1, v144
	v_mov_b32_e32 v0, 0xb00
	s_movk_i32 s4, 0x5000
	v_cndmask_b32_e32 v141, 0, v0, vcc
	v_lshlrev_b32_e32 v0, 2, v141
	v_lshl_add_u64 v[132:133], v[132:133], 0, v[0:1]
	v_add_co_u32_e32 v138, vcc, s4, v132
	s_mov_b32 s4, 0xb000
	s_nop 0
	v_addc_co_u32_e32 v139, vcc, 0, v133, vcc
	global_load_dword v136, v[132:133], off
	global_load_dword v137, v[138:139], off offset:2048
	v_add_co_u32_e32 v132, vcc, s4, v132
	v_add_u32_e32 v0, s88, v141
	s_nop 0
	v_addc_co_u32_e32 v133, vcc, 0, v133, vcc
	global_load_dword v138, v[132:133], off
	v_or_b32_e32 v132, v140, v0
	v_ashrrev_i32_e32 v133, 31, v132
	v_lshl_add_u64 v[132:133], v[132:133], 2, s[12:13]
	global_load_dword v139, v[132:133], off
	v_lshl_add_u32 v152, v135, 4, s78
	v_and_b32_e32 v135, 63, v131
	v_cmp_eq_u32_e32 vcc, 0, v144
	v_or_b32_e32 v0, s97, v135
	v_lshrrev_b32_e32 v0, 1, v0
	v_and_or_b32 v131, v0, 63, s55
	v_add_u32_e32 v132, s15, v131
	v_ashrrev_i32_e32 v133, 31, v132
	v_lshlrev_b64 v[132:133], 6, v[132:133]
	v_lshl_add_u64 v[132:133], s[10:11], 0, v[132:133]
	v_lshlrev_b32_e32 v0, 5, v144
	v_lshl_add_u64 v[132:133], v[132:133], 0, v[0:1]
	global_load_dwordx4 v[148:151], v[132:133], off offset:16
	global_load_dwordx4 v[140:143], v[132:133], off
	s_waitcnt vmcnt(2)
	ds_write_b128 v152, v[136:139]
	s_waitcnt vmcnt(0)
	v_add_f32_e32 v133, v150, v151
	v_add_f32_e32 v0, v140, v141
	v_add_f32_e32 v132, v142, v143
	v_add_f32_e32 v0, v0, v132
	v_add_f32_e32 v132, v148, v149
	v_add_f32_e32 v132, v132, v133
	v_add_f32_e32 v0, v0, v132
	v_lshlrev_b32_e32 v132, 2, v135
	v_xor_b32_e32 v132, 4, v132
	ds_bpermute_b32 v132, v132, v0
	s_and_saveexec_b64 s[4:5], vcc
	s_cbranch_execz .LBB0_922
	s_waitcnt lgkmcnt(0)
	v_add_f32_e32 v0, v0, v132
	v_mov_b32_e32 v132, 0x358637bd
	v_fmamk_f32 v0, v0, 0x3a800000, v132
	s_mov_b32 s6, 0x800000
	v_mul_f32_e32 v132, 0x4b800000, v0
	v_cmp_gt_f32_e32 vcc, s6, v0
	v_lshl_add_u32 v131, v131, 2, 0
	v_add_u32_e32 v131, 0x20000, v131
	v_cndmask_b32_e32 v0, v0, v132, vcc
	v_rsq_f32_e32 v0, v0
	s_nop 0
	v_mul_f32_e32 v132, 0x45800000, v0
	v_cndmask_b32_e32 v0, v0, v132, vcc
	ds_write_b32 v131, v0

.LBB0_1089:
	s_add_u32 s34, s84, 0x100
	v_mov_b32_e32 v2, 0
	s_addc_u32 s78, s85, 0
	s_mov_b32 s79, -2
	s_waitcnt lgkmcnt(0)
	v_mov_b32_e32 v3, v2
	v_mov_b32_e32 v4, v2
	v_mov_b32_e32 v5, v2
	v_mov_b32_e32 v6, v2
	v_mov_b32_e32 v7, v2
	v_mov_b32_e32 v8, v2
	v_mov_b32_e32 v9, v2
	v_mov_b32_e32 v18, v2
	v_mov_b32_e32 v19, v2
	v_mov_b32_e32 v20, v2
	v_mov_b32_e32 v21, v2
	v_mov_b32_e32 v22, v2
	v_mov_b32_e32 v23, v2
	v_mov_b32_e32 v24, v2
	v_mov_b32_e32 v25, v2
	v_mov_b32_e32 v34, v2
	v_mov_b32_e32 v35, v2
	v_mov_b32_e32 v36, v2
	v_mov_b32_e32 v37, v2
	v_mov_b32_e32 v38, v2
	v_mov_b32_e32 v39, v2
	v_mov_b32_e32 v40, v2
	v_mov_b32_e32 v41, v2
	v_mov_b32_e32 v50, v2
	v_mov_b32_e32 v51, v2
	v_mov_b32_e32 v52, v2
	v_mov_b32_e32 v53, v2
	v_mov_b32_e32 v54, v2
	v_mov_b32_e32 v55, v2
	v_mov_b32_e32 v56, v2
	v_mov_b32_e32 v57, v2
	v_mov_b32_e32 v10, v2
	v_mov_b32_e32 v11, v2
	v_mov_b32_e32 v12, v2
	v_mov_b32_e32 v13, v2
	v_mov_b32_e32 v14, v2
	v_mov_b32_e32 v15, v2
	v_mov_b32_e32 v16, v2
	v_mov_b32_e32 v17, v2
	v_mov_b32_e32 v26, v2
	v_mov_b32_e32 v27, v2
	v_mov_b32_e32 v28, v2
	v_mov_b32_e32 v29, v2
	v_mov_b32_e32 v30, v2
	v_mov_b32_e32 v31, v2
	v_mov_b32_e32 v32, v2
	v_mov_b32_e32 v33, v2
	v_mov_b32_e32 v42, v2
	v_mov_b32_e32 v43, v2
	v_mov_b32_e32 v44, v2
	v_mov_b32_e32 v45, v2
	v_mov_b32_e32 v46, v2
	v_mov_b32_e32 v47, v2
	v_mov_b32_e32 v48, v2
	v_mov_b32_e32 v49, v2
	v_mov_b32_e32 v58, v2
	v_mov_b32_e32 v59, v2
	v_mov_b32_e32 v60, v2
	v_mov_b32_e32 v61, v2
	v_mov_b32_e32 v62, v2
	v_mov_b32_e32 v63, v2
	v_mov_b32_e32 v64, v2
	v_mov_b32_e32 v65, v2
	v_mov_b32_e32 v66, v2
	v_mov_b32_e32 v67, v2
	v_mov_b32_e32 v68, v2
	v_mov_b32_e32 v69, v2
	v_mov_b32_e32 v70, v2
	v_mov_b32_e32 v71, v2
	v_mov_b32_e32 v72, v2
	v_mov_b32_e32 v73, v2
	v_mov_b32_e32 v82, v2
	v_mov_b32_e32 v83, v2
	v_mov_b32_e32 v84, v2
	v_mov_b32_e32 v85, v2
	v_mov_b32_e32 v86, v2
	v_mov_b32_e32 v87, v2
	v_mov_b32_e32 v88, v2
	v_mov_b32_e32 v89, v2
	v_mov_b32_e32 v98, v2
	v_mov_b32_e32 v99, v2
	v_mov_b32_e32 v100, v2
	v_mov_b32_e32 v101, v2
	v_mov_b32_e32 v102, v2
	v_mov_b32_e32 v103, v2
	v_mov_b32_e32 v104, v2
	v_mov_b32_e32 v105, v2
	v_mov_b32_e32 v114, v2
	v_mov_b32_e32 v115, v2
	v_mov_b32_e32 v116, v2
	v_mov_b32_e32 v117, v2
	v_mov_b32_e32 v118, v2
	v_mov_b32_e32 v119, v2
	v_mov_b32_e32 v120, v2
	v_mov_b32_e32 v121, v2
	v_mov_b32_e32 v74, v2
	v_mov_b32_e32 v75, v2
	v_mov_b32_e32 v76, v2
	v_mov_b32_e32 v77, v2
	v_mov_b32_e32 v78, v2
	v_mov_b32_e32 v79, v2
	v_mov_b32_e32 v80, v2
	v_mov_b32_e32 v81, v2
	v_mov_b32_e32 v90, v2
	v_mov_b32_e32 v91, v2
	v_mov_b32_e32 v92, v2
	v_mov_b32_e32 v93, v2
	v_mov_b32_e32 v94, v2
	v_mov_b32_e32 v95, v2
	v_mov_b32_e32 v96, v2
	v_mov_b32_e32 v97, v2
	v_mov_b32_e32 v106, v2
	v_mov_b32_e32 v107, v2
	v_mov_b32_e32 v108, v2
	v_mov_b32_e32 v109, v2
	v_mov_b32_e32 v110, v2
	v_mov_b32_e32 v111, v2
	v_mov_b32_e32 v112, v2
	v_mov_b32_e32 v113, v2
	v_mov_b32_e32 v122, v2
	v_mov_b32_e32 v123, v2
	v_mov_b32_e32 v124, v2
	v_mov_b32_e32 v125, v2
	v_mov_b32_e32 v126, v2
	v_mov_b32_e32 v127, v2
	v_mov_b32_e32 v128, v2
	v_mov_b32_e32 v129, v2
	s_add_i32 s90, 0, 0x10000
	v_add_u32_e32 v142, s90, v212
	v_add_u32_e32 v189, 0x10000, v212
	ds_read_b128 v[130:133], v142
	ds_read_b128 v[134:137], v142 offset:1024
	ds_read_b128 v[138:141], v142 offset:2048
	ds_read_b128 v[142:145], v142 offset:3072
	s_add_u32 s84, s16, 0x100
	s_addc_u32 s85, s17, 0
	s_cmp_eq_u32 s79, 40
	s_cselect_b32 s89, s5, s85
	s_cselect_b32 s88, s4, s84
	s_cselect_b32 s87, s7, s78
	s_cselect_b32 s86, s6, s34
.LBB0_1090:
	v_lshl_add_u64 v[178:179], s[16:17], 0, v[196:197]
	s_add_i32 m0, s39, 0xc000
	ds_read_b128 v[146:149], v213
	ds_read_b128 v[150:153], v213 offset:1024
	ds_read_b128 v[154:157], v213 offset:2048
	ds_read_b128 v[158:161], v213 offset:3072
	ds_read_b128 v[162:165], v213 offset:4096
	ds_read_b128 v[166:169], v213 offset:5120
	ds_read_b128 v[170:173], v213 offset:6144
	ds_read_b128 v[174:177], v213 offset:7168
	global_load_lds_dwordx4 v[178:179], off
	s_add_i32 m0, s39, 0xe000
	v_lshl_add_u64 v[178:179], s[16:17], 0, v[198:199]
	global_load_lds_dwordx4 v[178:179], off
	s_waitcnt lgkmcnt(8)
	s_barrier
	s_waitcnt lgkmcnt(0)
	v_mfma_f32_16x16x32_bf16 v[126:129], v[130:133], v[146:149], v[126:129]
	v_mfma_f32_16x16x32_bf16 v[122:125], v[138:141], v[146:149], v[122:125]
	v_mfma_f32_16x16x32_bf16 v[110:113], v[130:133], v[154:157], v[110:113]
	v_mfma_f32_16x16x32_bf16 v[106:109], v[138:141], v[154:157], v[106:109]
	v_mfma_f32_16x16x32_bf16 v[94:97], v[130:133], v[162:165], v[94:97]
	v_mfma_f32_16x16x32_bf16 v[90:93], v[138:141], v[162:165], v[90:93]
	v_mfma_f32_16x16x32_bf16 v[78:81], v[130:133], v[170:173], v[78:81]
	v_mfma_f32_16x16x32_bf16 v[74:77], v[138:141], v[170:173], v[74:77]
	v_mfma_f32_16x16x32_bf16 v[126:129], v[134:137], v[150:153], v[126:129]
	v_mfma_f32_16x16x32_bf16 v[122:125], v[142:145], v[150:153], v[122:125]
	v_mfma_f32_16x16x32_bf16 v[110:113], v[134:137], v[158:161], v[110:113]
	v_mfma_f32_16x16x32_bf16 v[106:109], v[142:145], v[158:161], v[106:109]
	v_mfma_f32_16x16x32_bf16 v[94:97], v[134:137], v[166:169], v[94:97]
	v_mfma_f32_16x16x32_bf16 v[90:93], v[142:145], v[166:169], v[90:93]
	v_mfma_f32_16x16x32_bf16 v[78:81], v[134:137], v[174:177], v[78:81]
	v_mfma_f32_16x16x32_bf16 v[74:77], v[142:145], v[174:177], v[74:77]
	s_barrier
	s_add_i32 s91, 0, 0x14000
	s_add_i32 s16, s90, s38
	ds_read_b128 v[178:181], v189 offset:16384
	ds_read_b128 v[182:185], v189 offset:17408
	ds_read_b128 v[200:203], v189 offset:18432
	ds_read_b128 v[204:207], v189 offset:19456
	s_mov_b32 m0, s16
	global_load_lds_dwordx4 v0, s[86:87]
	s_add_i32 m0, s16, 0x2000
	s_nop 0
	global_load_lds_dwordx4 v194, s[86:87]
	s_barrier
	s_waitcnt lgkmcnt(0)
	v_mfma_f32_16x16x32_bf16 v[118:121], v[178:181], v[146:149], v[118:121]
	v_mfma_f32_16x16x32_bf16 v[114:117], v[200:203], v[146:149], v[114:117]
	v_mfma_f32_16x16x32_bf16 v[102:105], v[178:181], v[154:157], v[102:105]
	v_mfma_f32_16x16x32_bf16 v[98:101], v[200:203], v[154:157], v[98:101]
	v_mfma_f32_16x16x32_bf16 v[86:89], v[178:181], v[162:165], v[86:89]
	v_mfma_f32_16x16x32_bf16 v[82:85], v[200:203], v[162:165], v[82:85]
	v_mfma_f32_16x16x32_bf16 v[70:73], v[178:181], v[170:173], v[70:73]
	v_mfma_f32_16x16x32_bf16 v[66:69], v[200:203], v[170:173], v[66:69]
	v_mfma_f32_16x16x32_bf16 v[118:121], v[182:185], v[150:153], v[118:121]
	v_mfma_f32_16x16x32_bf16 v[114:117], v[204:207], v[150:153], v[114:117]
	v_mfma_f32_16x16x32_bf16 v[102:105], v[182:185], v[158:161], v[102:105]
	v_mfma_f32_16x16x32_bf16 v[98:101], v[204:207], v[158:161], v[98:101]
	v_mfma_f32_16x16x32_bf16 v[86:89], v[182:185], v[166:169], v[86:89]
	v_mfma_f32_16x16x32_bf16 v[82:85], v[204:207], v[166:169], v[82:85]
	v_mfma_f32_16x16x32_bf16 v[70:73], v[182:185], v[174:177], v[70:73]
	v_mfma_f32_16x16x32_bf16 v[66:69], v[204:207], v[174:177], v[66:69]
	s_mov_b32 m0, s39
	s_mov_b64 s[100:101], s[88:89]
	s_barrier
	ds_read_b128 v[146:149], v213 offset:16384
	ds_read_b128 v[150:153], v213 offset:17408
	ds_read_b128 v[154:157], v213 offset:18432
	ds_read_b128 v[158:161], v213 offset:19456
	ds_read_b128 v[162:165], v213 offset:20480
	ds_read_b128 v[166:169], v213 offset:21504
	ds_read_b128 v[170:173], v213 offset:22528
	ds_read_b128 v[174:177], v213 offset:23552
	global_load_lds_dwordx4 v190, s[100:101]
	s_mov_b32 m0, s42
	s_nop 0
	global_load_lds_dwordx4 v192, s[100:101]
	s_waitcnt vmcnt(10)
	s_barrier
	s_waitcnt lgkmcnt(0)
	v_mfma_f32_16x16x32_bf16 v[62:65], v[130:133], v[146:149], v[62:65]
	v_mfma_f32_16x16x32_bf16 v[58:61], v[138:141], v[146:149], v[58:61]
	v_mfma_f32_16x16x32_bf16 v[46:49], v[130:133], v[154:157], v[46:49]
	v_mfma_f32_16x16x32_bf16 v[42:45], v[138:141], v[154:157], v[42:45]
	v_mfma_f32_16x16x32_bf16 v[30:33], v[130:133], v[162:165], v[30:33]
	v_mfma_f32_16x16x32_bf16 v[26:29], v[138:141], v[162:165], v[26:29]
	v_mfma_f32_16x16x32_bf16 v[14:17], v[130:133], v[170:173], v[14:17]
	v_mfma_f32_16x16x32_bf16 v[10:13], v[138:141], v[170:173], v[10:13]
	v_mfma_f32_16x16x32_bf16 v[62:65], v[134:137], v[150:153], v[62:65]
	v_mfma_f32_16x16x32_bf16 v[58:61], v[142:145], v[150:153], v[58:61]
	v_mfma_f32_16x16x32_bf16 v[46:49], v[134:137], v[158:161], v[46:49]
	v_mfma_f32_16x16x32_bf16 v[42:45], v[142:145], v[158:161], v[42:45]
	v_mfma_f32_16x16x32_bf16 v[30:33], v[134:137], v[166:169], v[30:33]
	v_mfma_f32_16x16x32_bf16 v[26:29], v[142:145], v[166:169], v[26:29]
	v_mfma_f32_16x16x32_bf16 v[14:17], v[134:137], v[174:177], v[14:17]
	v_mfma_f32_16x16x32_bf16 v[10:13], v[142:145], v[174:177], v[10:13]
	s_barrier
	s_add_u32 s16, s86, 0xb0000
	s_addc_u32 s17, s87, 0
	s_add_i32 s90, s91, s38
	s_mov_b32 m0, s90
	s_nop 0
	global_load_lds_dwordx4 v0, s[16:17]
	s_add_i32 m0, s90, 0x2000
	s_nop 0
	global_load_lds_dwordx4 v194, s[16:17]
	s_add_i32 s90, 0, 0x18000
	v_add_u32_e32 v142, s90, v212
	ds_read_b128 v[130:133], v142
	ds_read_b128 v[134:137], v142 offset:1024
	ds_read_b128 v[138:141], v142 offset:2048
	ds_read_b128 v[142:145], v142 offset:3072
	s_waitcnt vmcnt(6)
	s_barrier
	v_mfma_f32_16x16x32_bf16 v[54:57], v[178:181], v[146:149], v[54:57]
	v_mfma_f32_16x16x32_bf16 v[50:53], v[200:203], v[146:149], v[50:53]
	v_mfma_f32_16x16x32_bf16 v[38:41], v[178:181], v[154:157], v[38:41]
	v_mfma_f32_16x16x32_bf16 v[34:37], v[200:203], v[154:157], v[34:37]
	v_mfma_f32_16x16x32_bf16 v[22:25], v[178:181], v[162:165], v[22:25]
	v_mfma_f32_16x16x32_bf16 v[18:21], v[200:203], v[162:165], v[18:21]
	v_mfma_f32_16x16x32_bf16 v[6:9], v[178:181], v[170:173], v[6:9]
	v_mfma_f32_16x16x32_bf16 v[2:5], v[200:203], v[170:173], v[2:5]
	v_mfma_f32_16x16x32_bf16 v[54:57], v[182:185], v[150:153], v[54:57]
	v_mfma_f32_16x16x32_bf16 v[50:53], v[204:207], v[150:153], v[50:53]
	v_mfma_f32_16x16x32_bf16 v[38:41], v[182:185], v[158:161], v[38:41]
	v_mfma_f32_16x16x32_bf16 v[34:37], v[204:207], v[158:161], v[34:37]
	v_mfma_f32_16x16x32_bf16 v[22:25], v[182:185], v[166:169], v[22:25]
	v_mfma_f32_16x16x32_bf16 v[18:21], v[204:207], v[166:169], v[18:21]
	v_mfma_f32_16x16x32_bf16 v[6:9], v[182:185], v[174:177], v[6:9]
	v_mfma_f32_16x16x32_bf16 v[2:5], v[204:207], v[174:177], v[2:5]
	s_barrier
	s_add_u32 s16, s88, 0xb0000
	s_addc_u32 s17, s89, 0
	s_mov_b32 m0, s43
	ds_read_b128 v[146:149], v213 offset:32768
	ds_read_b128 v[150:153], v213 offset:33792
	ds_read_b128 v[154:157], v213 offset:34816
	ds_read_b128 v[158:161], v213 offset:35840
	ds_read_b128 v[162:165], v213 offset:36864
	ds_read_b128 v[166:169], v213 offset:37888
	ds_read_b128 v[170:173], v213 offset:38912
	ds_read_b128 v[174:177], v213 offset:39936
	global_load_lds_dwordx4 v190, s[16:17]
	s_mov_b32 m0, s44
	s_nop 0
	global_load_lds_dwordx4 v192, s[16:17]
	s_waitcnt lgkmcnt(8)
	s_barrier
	s_waitcnt lgkmcnt(0)
	v_mfma_f32_16x16x32_bf16 v[126:129], v[130:133], v[146:149], v[126:129]
	v_mfma_f32_16x16x32_bf16 v[122:125], v[138:141], v[146:149], v[122:125]
	v_mfma_f32_16x16x32_bf16 v[110:113], v[130:133], v[154:157], v[110:113]
	v_mfma_f32_16x16x32_bf16 v[106:109], v[138:141], v[154:157], v[106:109]
	v_mfma_f32_16x16x32_bf16 v[94:97], v[130:133], v[162:165], v[94:97]
	v_mfma_f32_16x16x32_bf16 v[90:93], v[138:141], v[162:165], v[90:93]
	v_mfma_f32_16x16x32_bf16 v[78:81], v[130:133], v[170:173], v[78:81]
	v_mfma_f32_16x16x32_bf16 v[74:77], v[138:141], v[170:173], v[74:77]
	v_mfma_f32_16x16x32_bf16 v[126:129], v[134:137], v[150:153], v[126:129]
	v_mfma_f32_16x16x32_bf16 v[122:125], v[142:145], v[150:153], v[122:125]
	v_mfma_f32_16x16x32_bf16 v[110:113], v[134:137], v[158:161], v[110:113]
	v_mfma_f32_16x16x32_bf16 v[106:109], v[142:145], v[158:161], v[106:109]
	v_mfma_f32_16x16x32_bf16 v[94:97], v[134:137], v[166:169], v[94:97]
	v_mfma_f32_16x16x32_bf16 v[90:93], v[142:145], v[166:169], v[90:93]
	v_mfma_f32_16x16x32_bf16 v[78:81], v[134:137], v[174:177], v[78:81]
	v_mfma_f32_16x16x32_bf16 v[74:77], v[142:145], v[174:177], v[74:77]
	s_barrier
	s_add_i32 s88, 0, 0x1c000
	s_add_i32 s16, s90, s38
	v_add_u32_e32 v204, s88, v212
	s_mov_b32 m0, s16
	ds_read_b128 v[178:181], v204
	ds_read_b128 v[182:185], v204 offset:1024
	ds_read_b128 v[200:203], v204 offset:2048
	ds_read_b128 v[204:207], v204 offset:3072
	s_add_u32 s98, s86, s40
	s_addc_u32 s99, s87, s41
	global_load_lds_dwordx4 v0, s[98:99]
	s_add_i32 m0, s16, 0x2000
	s_add_u32 s98, s86, s40
	s_addc_u32 s99, s87, s41
	global_load_lds_dwordx4 v194, s[98:99]
	s_barrier
	s_waitcnt lgkmcnt(0)
	v_mfma_f32_16x16x32_bf16 v[118:121], v[178:181], v[146:149], v[118:121]
	v_mfma_f32_16x16x32_bf16 v[114:117], v[200:203], v[146:149], v[114:117]
	v_mfma_f32_16x16x32_bf16 v[102:105], v[178:181], v[154:157], v[102:105]
	v_mfma_f32_16x16x32_bf16 v[98:101], v[200:203], v[154:157], v[98:101]
	v_mfma_f32_16x16x32_bf16 v[86:89], v[178:181], v[162:165], v[86:89]
	v_mfma_f32_16x16x32_bf16 v[82:85], v[200:203], v[162:165], v[82:85]
	v_mfma_f32_16x16x32_bf16 v[70:73], v[178:181], v[170:173], v[70:73]
	v_mfma_f32_16x16x32_bf16 v[66:69], v[200:203], v[170:173], v[66:69]
	v_mfma_f32_16x16x32_bf16 v[118:121], v[182:185], v[150:153], v[118:121]
	v_mfma_f32_16x16x32_bf16 v[114:117], v[204:207], v[150:153], v[114:117]
	v_mfma_f32_16x16x32_bf16 v[102:105], v[182:185], v[158:161], v[102:105]
	v_mfma_f32_16x16x32_bf16 v[98:101], v[204:207], v[158:161], v[98:101]
	v_mfma_f32_16x16x32_bf16 v[86:89], v[182:185], v[166:169], v[86:89]
	v_mfma_f32_16x16x32_bf16 v[82:85], v[204:207], v[166:169], v[82:85]
	v_mfma_f32_16x16x32_bf16 v[70:73], v[182:185], v[174:177], v[70:73]
	v_mfma_f32_16x16x32_bf16 v[66:69], v[204:207], v[174:177], v[66:69]
	s_mov_b32 m0, s60
	s_barrier
	ds_read_b128 v[146:149], v213 offset:49152
	ds_read_b128 v[150:153], v213 offset:50176
	ds_read_b128 v[154:157], v213 offset:51200
	ds_read_b128 v[158:161], v213 offset:52224
	ds_read_b128 v[162:165], v213 offset:53248
	ds_read_b128 v[166:169], v213 offset:54272
	ds_read_b128 v[170:173], v213 offset:55296
	ds_read_b128 v[174:177], v213 offset:56320
	s_add_u32 s98, s100, s40
	s_addc_u32 s99, s101, s41
	global_load_lds_dwordx4 v190, s[98:99]
	s_mov_b32 m0, s61
	s_add_u32 s98, s100, s40
	s_addc_u32 s99, s101, s41
	global_load_lds_dwordx4 v192, s[98:99]
	s_waitcnt vmcnt(10)
	s_barrier
	s_waitcnt lgkmcnt(0)
	v_mfma_f32_16x16x32_bf16 v[62:65], v[130:133], v[146:149], v[62:65]
	v_mfma_f32_16x16x32_bf16 v[58:61], v[138:141], v[146:149], v[58:61]
	v_mfma_f32_16x16x32_bf16 v[46:49], v[130:133], v[154:157], v[46:49]
	v_mfma_f32_16x16x32_bf16 v[42:45], v[138:141], v[154:157], v[42:45]
	v_mfma_f32_16x16x32_bf16 v[30:33], v[130:133], v[162:165], v[30:33]
	v_mfma_f32_16x16x32_bf16 v[26:29], v[138:141], v[162:165], v[26:29]
	v_mfma_f32_16x16x32_bf16 v[14:17], v[130:133], v[170:173], v[14:17]
	v_mfma_f32_16x16x32_bf16 v[10:13], v[138:141], v[170:173], v[10:13]
	v_mfma_f32_16x16x32_bf16 v[62:65], v[134:137], v[150:153], v[62:65]
	v_mfma_f32_16x16x32_bf16 v[58:61], v[142:145], v[150:153], v[58:61]
	v_mfma_f32_16x16x32_bf16 v[46:49], v[134:137], v[158:161], v[46:49]
	v_mfma_f32_16x16x32_bf16 v[42:45], v[142:145], v[158:161], v[42:45]
	v_mfma_f32_16x16x32_bf16 v[30:33], v[134:137], v[166:169], v[30:33]
	v_mfma_f32_16x16x32_bf16 v[26:29], v[142:145], v[166:169], v[26:29]
	v_mfma_f32_16x16x32_bf16 v[14:17], v[134:137], v[174:177], v[14:17]
	v_mfma_f32_16x16x32_bf16 v[10:13], v[142:145], v[174:177], v[10:13]
	s_barrier
	s_add_u32 s16, s86, 0xb0080
	s_addc_u32 s17, s87, 0
	s_add_i32 s86, s88, s38
	s_mov_b32 m0, s86
	s_nop 0
	global_load_lds_dwordx4 v0, s[16:17]
	s_add_i32 m0, s86, 0x2000
	s_nop 0
	global_load_lds_dwordx4 v194, s[16:17]
	s_add_i32 s90, 0, 0x10000
	ds_read_b128 v[130:133], v189
	ds_read_b128 v[134:137], v189 offset:1024
	ds_read_b128 v[138:141], v189 offset:2048
	ds_read_b128 v[142:145], v189 offset:3072
	s_waitcnt vmcnt(6)
	s_barrier
	v_mfma_f32_16x16x32_bf16 v[54:57], v[178:181], v[146:149], v[54:57]
	v_mfma_f32_16x16x32_bf16 v[50:53], v[200:203], v[146:149], v[50:53]
	v_mfma_f32_16x16x32_bf16 v[38:41], v[178:181], v[154:157], v[38:41]
	v_mfma_f32_16x16x32_bf16 v[34:37], v[200:203], v[154:157], v[34:37]
	v_mfma_f32_16x16x32_bf16 v[22:25], v[178:181], v[162:165], v[22:25]
	v_mfma_f32_16x16x32_bf16 v[18:21], v[200:203], v[162:165], v[18:21]
	v_mfma_f32_16x16x32_bf16 v[6:9], v[178:181], v[170:173], v[6:9]
	v_mfma_f32_16x16x32_bf16 v[2:5], v[200:203], v[170:173], v[2:5]
	v_mfma_f32_16x16x32_bf16 v[54:57], v[182:185], v[150:153], v[54:57]
	v_mfma_f32_16x16x32_bf16 v[50:53], v[204:207], v[150:153], v[50:53]
	v_mfma_f32_16x16x32_bf16 v[38:41], v[182:185], v[158:161], v[38:41]
	v_mfma_f32_16x16x32_bf16 v[34:37], v[204:207], v[158:161], v[34:37]
	v_mfma_f32_16x16x32_bf16 v[22:25], v[182:185], v[166:169], v[22:25]
	v_mfma_f32_16x16x32_bf16 v[18:21], v[204:207], v[166:169], v[18:21]
	v_mfma_f32_16x16x32_bf16 v[6:9], v[182:185], v[174:177], v[6:9]
	v_mfma_f32_16x16x32_bf16 v[2:5], v[204:207], v[174:177], v[2:5]
	s_add_i32 s79, s79, 2
	s_add_u32 s34, s34, 0x100
	s_addc_u32 s78, s78, 0
	s_mov_b64 s[16:17], s[84:85]
	s_add_u32 s84, s16, 0x100
	s_addc_u32 s85, s17, 0
	s_cmp_eq_u32 s79, 40
	s_cselect_b32 s89, s5, s85
	s_cselect_b32 s88, s4, s84
	s_cselect_b32 s87, s7, s78
	s_cselect_b32 s86, s6, s34
	s_cmp_gt_u32 s79, 41
	s_barrier
	s_cbranch_scc0 .LBB0_1090
	s_waitcnt lgkmcnt(0)
	s_lshl_b32 s16, s23, 8
	v_mov_b32_e32 v186, v252
	s_add_i32 s16, s16, s47
	s_nop 0
	v_and_or_b32 v202, v186, 15, s16
	s_lshl_b32 s16, s22, 8
	s_or_b32 s16, s16, s55
	v_lshrrev_b32_e32 v130, 1, v186
	v_and_or_b32 v200, v130, 24, s16
	v_ashrrev_i32_e32 v201, 31, v200
	v_ashrrev_i32_e32 v203, 31, v202
	v_lshl_add_u64 v[204:205], v[200:201], 2, s[12:13]
	v_lshlrev_b64 v[130:131], 12, v[202:203]
	v_lshl_add_u64 v[130:131], v[204:205], 0, v[130:131]
	global_load_dwordx4 v[216:219], v[130:131], off offset:16
	global_load_dwordx4 v[220:223], v[130:131], off
	global_load_dwordx4 v[178:181], v[130:131], off offset:528
	global_load_dwordx4 v[182:185], v[130:131], off offset:512
	v_or_b32_e32 v210, 16, v202
	v_ashrrev_i32_e32 v211, 31, v210
	v_lshlrev_b64 v[130:131], 12, v[210:211]
	v_or_b32_e32 v208, 32, v202
	v_lshl_add_u64 v[130:131], v[204:205], 0, v[130:131]
	v_ashrrev_i32_e32 v209, 31, v208
	global_load_dwordx4 v[170:173], v[130:131], off offset:16
	global_load_dwordx4 v[174:177], v[130:131], off
	global_load_dwordx4 v[162:165], v[130:131], off offset:528
	global_load_dwordx4 v[166:169], v[130:131], off offset:512
	v_lshlrev_b64 v[130:131], 12, v[208:209]
	v_or_b32_e32 v206, 48, v202
	v_lshl_add_u64 v[130:131], v[204:205], 0, v[130:131]
	v_ashrrev_i32_e32 v207, 31, v206
	global_load_dwordx4 v[154:157], v[130:131], off offset:16
	global_load_dwordx4 v[158:161], v[130:131], off
	global_load_dwordx4 v[138:141], v[130:131], off offset:528
	global_load_dwordx4 v[142:145], v[130:131], off offset:512
	v_lshlrev_b64 v[130:131], 12, v[206:207]
	v_lshl_add_u64 v[134:135], v[204:205], 0, v[130:131]
	global_load_dwordx4 v[146:149], v[134:135], off offset:16
	global_load_dwordx4 v[150:153], v[134:135], off
	global_load_dwordx4 v[130:133], v[134:135], off offset:528
	s_nop 0
	global_load_dwordx4 v[134:137], v[134:135], off offset:512
	v_and_b32_e32 v186, 63, v186
	v_lshlrev_b32_e32 v187, 2, v186
	v_xor_b32_e32 v215, 64, v187
	v_xor_b32_e32 v214, 0x80, v187
	v_cmp_gt_u32_e32 vcc, 16, v186
	v_lshlrev_b64 v[186:187], 10, v[202:203]
	v_lshl_add_u64 v[186:187], v[186:187], 0, v[200:201]
	s_lshl_b32 s16, s22, 2
	s_ashr_i32 s17, s16, 31
	s_waitcnt vmcnt(0)
	v_pk_add_f32 v[124:125], v[124:125], v[218:219]
	v_pk_add_f32 v[128:129], v[128:129], v[222:223]
	v_pk_add_f32 v[126:127], v[126:127], v[220:221]
	v_pk_mul_f32 v[218:219], v[128:129], v[128:129]
	v_pk_mul_f32 v[220:221], v[126:127], v[126:127]
	v_pk_add_f32 v[122:123], v[122:123], v[216:217]
	v_lshl_add_u64 v[216:217], v[186:187], 2, s[14:15]
	v_add_f32_e32 v220, v220, v221
	v_add_f32_e32 v218, v218, v219
	global_store_dwordx4 v[216:217], v[126:129], off
	global_store_dwordx4 v[216:217], v[122:125], off offset:16
	v_add_f32_e32 v222, v220, v218
	v_pk_mul_f32 v[220:221], v[122:123], v[122:123]
	v_cvt_pk_bf16_f32 v126, v126, v127
	v_cvt_pk_bf16_f32 v127, v128, v129
	v_cvt_pk_bf16_f32 v128, v122, v123
	v_cvt_pk_bf16_f32 v129, v124, v125
	v_lshl_add_u64 v[122:123], v[186:187], 1, s[80:81]
	v_pk_add_f32 v[120:121], v[120:121], v[184:185]
	v_pk_add_f32 v[118:119], v[118:119], v[182:183]
	v_pk_mul_f32 v[218:219], v[124:125], v[124:125]
	global_store_dwordx4 v[122:123], v[126:129], off
	v_pk_mul_f32 v[124:125], v[120:121], v[120:121]
	v_pk_add_f32 v[116:117], v[116:117], v[180:181]
	v_pk_mul_f32 v[126:127], v[118:119], v[118:119]
	v_pk_add_f32 v[114:115], v[114:115], v[178:179]
	v_add_f32_e32 v126, v126, v127
	v_add_f32_e32 v124, v124, v125
	v_add_f32_e32 v128, v126, v124
	v_pk_mul_f32 v[124:125], v[116:117], v[116:117]
	v_pk_mul_f32 v[126:127], v[114:115], v[114:115]
	v_add_f32_e32 v220, v220, v221
	v_add_f32_e32 v218, v218, v219
	v_add_f32_e32 v126, v126, v127
	v_add_f32_e32 v124, v124, v125
	v_add_f32_e32 v218, v220, v218
	v_add_f32_e32 v124, v126, v124
	v_add_f32_e32 v218, v222, v218
	v_add_f32_e32 v124, v128, v124
	v_add_f32_e32 v124, v218, v124
	global_store_dwordx4 v[216:217], v[118:121], off offset:512
	global_store_dwordx4 v[216:217], v[114:117], off offset:528
	s_nop 0
	v_cvt_pk_bf16_f32 v118, v118, v119
	v_cvt_pk_bf16_f32 v119, v120, v121
	v_cvt_pk_bf16_f32 v120, v114, v115
	ds_bpermute_b32 v114, v215, v124
	v_cvt_pk_bf16_f32 v121, v116, v117
	global_store_dwordx4 v[122:123], v[118:121], off offset:256
	s_waitcnt lgkmcnt(0)
	v_add_f32_e32 v114, v124, v114
	ds_bpermute_b32 v115, v214, v114
	s_and_saveexec_b64 s[22:23], vcc
	s_cbranch_execz .LBB0_1093
	v_lshlrev_b64 v[116:117], 6, v[202:203]
	v_lshl_add_u64 v[116:117], s[82:83], 0, v[116:117]
	v_lshl_add_u64 v[116:117], s[16:17], 2, v[116:117]
	s_lshl_b32 s34, s45, 2
	v_lshl_add_u64 v[116:117], v[116:117], 0, s[34:35]
	s_waitcnt lgkmcnt(0)
	v_add_f32_e32 v114, v114, v115
	global_store_dword v[116:117], v114, off

.LBB0_1208:
	s_ashr_i32 s13, s12, 31
	v_cmp_lt_i64_e32 vcc, s[14:15], v[230:231]
	s_lshl_b64 s[14:15], s[12:13], 19
	s_add_u32 s14, s80, s14
	s_addc_u32 s15, s81, s15
	s_and_b64 s[16:17], vcc, exec
	s_cselect_b32 s13, s15, s89
	s_cselect_b32 s22, s14, s88
	s_ashr_i32 s7, s6, 31
	s_lshl_b64 s[16:17], s[6:7], 19
	s_add_u32 s16, s36, s16
	s_addc_u32 s17, s37, s17
	s_and_b64 s[92:93], vcc, exec
	s_cselect_b32 s7, s17, s91
	s_cselect_b32 s23, s16, s90
	s_add_u32 s88, s88, 0x40080
	s_addc_u32 s89, s89, 0
	s_add_u32 s34, s90, 0x100
	v_mov_b32_e32 v2, 0
	s_addc_u32 s79, s91, 0
	s_mov_b32 s85, -2
	v_mov_b32_e32 v3, v2
	v_mov_b32_e32 v4, v2
	v_mov_b32_e32 v5, v2
	v_mov_b32_e32 v6, v2
	v_mov_b32_e32 v7, v2
	v_mov_b32_e32 v8, v2
	v_mov_b32_e32 v9, v2
	v_mov_b32_e32 v18, v2
	v_mov_b32_e32 v19, v2
	v_mov_b32_e32 v20, v2
	v_mov_b32_e32 v21, v2
	v_mov_b32_e32 v22, v2
	v_mov_b32_e32 v23, v2
	v_mov_b32_e32 v24, v2
	v_mov_b32_e32 v25, v2
	v_mov_b32_e32 v34, v2
	v_mov_b32_e32 v35, v2
	v_mov_b32_e32 v36, v2
	v_mov_b32_e32 v37, v2
	v_mov_b32_e32 v38, v2
	v_mov_b32_e32 v39, v2
	v_mov_b32_e32 v40, v2
	v_mov_b32_e32 v41, v2
	v_mov_b32_e32 v50, v2
	v_mov_b32_e32 v51, v2
	v_mov_b32_e32 v52, v2
	v_mov_b32_e32 v53, v2
	v_mov_b32_e32 v54, v2
	v_mov_b32_e32 v55, v2
	v_mov_b32_e32 v56, v2
	v_mov_b32_e32 v57, v2
	v_mov_b32_e32 v10, v2
	v_mov_b32_e32 v11, v2
	v_mov_b32_e32 v12, v2
	v_mov_b32_e32 v13, v2
	v_mov_b32_e32 v14, v2
	v_mov_b32_e32 v15, v2
	v_mov_b32_e32 v16, v2
	v_mov_b32_e32 v17, v2
	v_mov_b32_e32 v26, v2
	v_mov_b32_e32 v27, v2
	v_mov_b32_e32 v28, v2
	v_mov_b32_e32 v29, v2
	v_mov_b32_e32 v30, v2
	v_mov_b32_e32 v31, v2
	v_mov_b32_e32 v32, v2
	v_mov_b32_e32 v33, v2
	v_mov_b32_e32 v42, v2
	v_mov_b32_e32 v43, v2
	v_mov_b32_e32 v44, v2
	v_mov_b32_e32 v45, v2
	v_mov_b32_e32 v46, v2
	v_mov_b32_e32 v47, v2
	v_mov_b32_e32 v48, v2
	v_mov_b32_e32 v49, v2
	v_mov_b32_e32 v58, v2
	v_mov_b32_e32 v59, v2
	v_mov_b32_e32 v60, v2
	v_mov_b32_e32 v61, v2
	v_mov_b32_e32 v62, v2
	v_mov_b32_e32 v63, v2
	v_mov_b32_e32 v64, v2
	v_mov_b32_e32 v65, v2
	v_mov_b32_e32 v66, v2
	v_mov_b32_e32 v67, v2
	v_mov_b32_e32 v68, v2
	v_mov_b32_e32 v69, v2
	v_mov_b32_e32 v70, v2
	v_mov_b32_e32 v71, v2
	v_mov_b32_e32 v72, v2
	v_mov_b32_e32 v73, v2
	v_mov_b32_e32 v82, v2
	v_mov_b32_e32 v83, v2
	v_mov_b32_e32 v84, v2
	v_mov_b32_e32 v85, v2
	v_mov_b32_e32 v86, v2
	v_mov_b32_e32 v87, v2
	v_mov_b32_e32 v88, v2
	v_mov_b32_e32 v89, v2
	v_mov_b32_e32 v98, v2
	v_mov_b32_e32 v99, v2
	v_mov_b32_e32 v100, v2
	v_mov_b32_e32 v101, v2
	v_mov_b32_e32 v102, v2
	v_mov_b32_e32 v103, v2
	v_mov_b32_e32 v104, v2
	v_mov_b32_e32 v105, v2
	v_mov_b32_e32 v114, v2
	v_mov_b32_e32 v115, v2
	v_mov_b32_e32 v116, v2
	v_mov_b32_e32 v117, v2
	v_mov_b32_e32 v118, v2
	v_mov_b32_e32 v119, v2
	v_mov_b32_e32 v120, v2
	v_mov_b32_e32 v121, v2
	v_mov_b32_e32 v74, v2
	v_mov_b32_e32 v75, v2
	v_mov_b32_e32 v76, v2
	v_mov_b32_e32 v77, v2
	v_mov_b32_e32 v78, v2
	v_mov_b32_e32 v79, v2
	v_mov_b32_e32 v80, v2
	v_mov_b32_e32 v81, v2
	v_mov_b32_e32 v90, v2
	v_mov_b32_e32 v91, v2
	v_mov_b32_e32 v92, v2
	v_mov_b32_e32 v93, v2
	v_mov_b32_e32 v94, v2
	v_mov_b32_e32 v95, v2
	v_mov_b32_e32 v96, v2
	v_mov_b32_e32 v97, v2
	v_mov_b32_e32 v106, v2
	v_mov_b32_e32 v107, v2
	v_mov_b32_e32 v108, v2
	v_mov_b32_e32 v109, v2
	v_mov_b32_e32 v110, v2
	v_mov_b32_e32 v111, v2
	v_mov_b32_e32 v112, v2
	v_mov_b32_e32 v113, v2
	v_mov_b32_e32 v122, v2
	v_mov_b32_e32 v123, v2
	v_mov_b32_e32 v124, v2
	v_mov_b32_e32 v125, v2
	v_mov_b32_e32 v126, v2
	v_mov_b32_e32 v127, v2
	v_mov_b32_e32 v128, v2
	v_mov_b32_e32 v129, v2
	s_waitcnt lgkmcnt(0)
	s_add_i32 s94, 0, 0x10000
	v_add_u32_e32 v0, s94, v170
	v_add_u32_e32 v189, 0x10000, v170
	ds_read_b128 v[130:133], v0
	ds_read_b128 v[134:137], v0 offset:1024
	ds_read_b128 v[138:141], v0 offset:2048
	ds_read_b128 v[142:145], v0 offset:3072
	s_add_u32 s87, s88, 0xfffc0080
	s_addc_u32 s90, s89, -1
	s_cmp_eq_u32 s85, 12
	s_cselect_b32 s93, s13, s90
	s_cselect_b32 s92, s22, s87
	s_cselect_b32 s91, s7, s79
	s_cselect_b32 s90, s23, s34
.LBB0_1209:
	s_waitcnt lgkmcnt(0)
	s_add_i32 m0, s39, 0xc000
	ds_read_b128 v[158:161], v171
	ds_read_b128 v[162:165], v171 offset:1024
	ds_read_b128 v[166:169], v171 offset:2048
	ds_read_b128 v[172:175], v171 offset:3072
	ds_read_b128 v[176:179], v171 offset:4096
	ds_read_b128 v[180:183], v171 offset:5120
	ds_read_b128 v[184:187], v171 offset:6144
	ds_read_b128 v[190:193], v171 offset:7168
	global_load_lds_dwordx4 v154, s[88:89]
	s_add_i32 m0, s39, 0xe000
	s_nop 0
	global_load_lds_dwordx4 v156, s[88:89]
	s_waitcnt lgkmcnt(8)
	s_barrier
	s_waitcnt lgkmcnt(0)
	v_mfma_f32_16x16x32_bf16 v[126:129], v[130:133], v[158:161], v[126:129]
	v_mfma_f32_16x16x32_bf16 v[122:125], v[138:141], v[158:161], v[122:125]
	v_mfma_f32_16x16x32_bf16 v[110:113], v[130:133], v[166:169], v[110:113]
	v_mfma_f32_16x16x32_bf16 v[106:109], v[138:141], v[166:169], v[106:109]
	v_mfma_f32_16x16x32_bf16 v[94:97], v[130:133], v[176:179], v[94:97]
	v_mfma_f32_16x16x32_bf16 v[90:93], v[138:141], v[176:179], v[90:93]
	v_mfma_f32_16x16x32_bf16 v[78:81], v[130:133], v[184:187], v[78:81]
	v_mfma_f32_16x16x32_bf16 v[74:77], v[138:141], v[184:187], v[74:77]
	v_mfma_f32_16x16x32_bf16 v[126:129], v[134:137], v[162:165], v[126:129]
	v_mfma_f32_16x16x32_bf16 v[122:125], v[142:145], v[162:165], v[122:125]
	v_mfma_f32_16x16x32_bf16 v[110:113], v[134:137], v[172:175], v[110:113]
	v_mfma_f32_16x16x32_bf16 v[106:109], v[142:145], v[172:175], v[106:109]
	v_mfma_f32_16x16x32_bf16 v[94:97], v[134:137], v[180:183], v[94:97]
	v_mfma_f32_16x16x32_bf16 v[90:93], v[142:145], v[180:183], v[90:93]
	v_mfma_f32_16x16x32_bf16 v[78:81], v[134:137], v[190:193], v[78:81]
	v_mfma_f32_16x16x32_bf16 v[74:77], v[142:145], v[190:193], v[74:77]
	s_barrier
	s_add_i32 s87, 0, 0x14000
	s_add_i32 s94, s94, s38
	s_mov_b32 m0, s94
	ds_read_b128 v[194:197], v189 offset:16384
	ds_read_b128 v[198:201], v189 offset:17408
	ds_read_b128 v[202:205], v189 offset:18432
	ds_read_b128 v[206:209], v189 offset:19456
	global_load_lds_dwordx4 v148, s[90:91]
	s_add_i32 m0, s94, 0x2000
	s_nop 0
	global_load_lds_dwordx4 v152, s[90:91]
	s_barrier
	s_waitcnt lgkmcnt(0)
	v_mfma_f32_16x16x32_bf16 v[118:121], v[194:197], v[158:161], v[118:121]
	v_mfma_f32_16x16x32_bf16 v[114:117], v[202:205], v[158:161], v[114:117]
	v_mfma_f32_16x16x32_bf16 v[102:105], v[194:197], v[166:169], v[102:105]
	v_mfma_f32_16x16x32_bf16 v[98:101], v[202:205], v[166:169], v[98:101]
	v_mfma_f32_16x16x32_bf16 v[86:89], v[194:197], v[176:179], v[86:89]
	v_mfma_f32_16x16x32_bf16 v[82:85], v[202:205], v[176:179], v[82:85]
	v_mfma_f32_16x16x32_bf16 v[70:73], v[194:197], v[184:187], v[70:73]
	v_mfma_f32_16x16x32_bf16 v[66:69], v[202:205], v[184:187], v[66:69]
	v_mfma_f32_16x16x32_bf16 v[118:121], v[198:201], v[162:165], v[118:121]
	v_mfma_f32_16x16x32_bf16 v[114:117], v[206:209], v[162:165], v[114:117]
	v_mfma_f32_16x16x32_bf16 v[102:105], v[198:201], v[172:175], v[102:105]
	v_mfma_f32_16x16x32_bf16 v[98:101], v[206:209], v[172:175], v[98:101]
	v_mfma_f32_16x16x32_bf16 v[86:89], v[198:201], v[180:183], v[86:89]
	v_mfma_f32_16x16x32_bf16 v[82:85], v[206:209], v[180:183], v[82:85]
	v_mfma_f32_16x16x32_bf16 v[70:73], v[198:201], v[190:193], v[70:73]
	v_mfma_f32_16x16x32_bf16 v[66:69], v[206:209], v[190:193], v[66:69]
	s_mov_b32 m0, s39
	s_mov_b64 s[100:101], s[92:93]
	s_barrier
	ds_read_b128 v[158:161], v171 offset:16384
	ds_read_b128 v[162:165], v171 offset:17408
	ds_read_b128 v[166:169], v171 offset:18432
	ds_read_b128 v[172:175], v171 offset:19456
	ds_read_b128 v[176:179], v171 offset:20480
	ds_read_b128 v[180:183], v171 offset:21504
	ds_read_b128 v[184:187], v171 offset:22528
	ds_read_b128 v[190:193], v171 offset:23552
	global_load_lds_dwordx4 v146, s[100:101]
	s_mov_b32 m0, s42
	s_nop 0
	global_load_lds_dwordx4 v150, s[100:101]
	s_waitcnt vmcnt(10)
	s_barrier
	s_waitcnt lgkmcnt(0)
	v_mfma_f32_16x16x32_bf16 v[62:65], v[130:133], v[158:161], v[62:65]
	v_mfma_f32_16x16x32_bf16 v[58:61], v[138:141], v[158:161], v[58:61]
	v_mfma_f32_16x16x32_bf16 v[46:49], v[130:133], v[166:169], v[46:49]
	v_mfma_f32_16x16x32_bf16 v[42:45], v[138:141], v[166:169], v[42:45]
	v_mfma_f32_16x16x32_bf16 v[30:33], v[130:133], v[176:179], v[30:33]
	v_mfma_f32_16x16x32_bf16 v[26:29], v[138:141], v[176:179], v[26:29]
	v_mfma_f32_16x16x32_bf16 v[14:17], v[130:133], v[184:187], v[14:17]
	v_mfma_f32_16x16x32_bf16 v[10:13], v[138:141], v[184:187], v[10:13]
	v_mfma_f32_16x16x32_bf16 v[62:65], v[134:137], v[162:165], v[62:65]
	v_mfma_f32_16x16x32_bf16 v[58:61], v[142:145], v[162:165], v[58:61]
	v_mfma_f32_16x16x32_bf16 v[46:49], v[134:137], v[172:175], v[46:49]
	v_mfma_f32_16x16x32_bf16 v[42:45], v[142:145], v[172:175], v[42:45]
	v_mfma_f32_16x16x32_bf16 v[30:33], v[134:137], v[180:183], v[30:33]
	v_mfma_f32_16x16x32_bf16 v[26:29], v[142:145], v[180:183], v[26:29]
	v_mfma_f32_16x16x32_bf16 v[14:17], v[134:137], v[190:193], v[14:17]
	v_mfma_f32_16x16x32_bf16 v[10:13], v[142:145], v[190:193], v[10:13]
	s_barrier
	s_add_u32 s94, s90, 0x40000
	s_addc_u32 s95, s91, 0
	s_add_i32 s87, s87, s38
	s_mov_b32 m0, s87
	s_nop 0
	global_load_lds_dwordx4 v148, s[94:95]
	s_add_i32 m0, s87, 0x2000
	s_nop 0
	global_load_lds_dwordx4 v152, s[94:95]
	s_add_i32 s87, 0, 0x18000
	ds_read_b128 v[130:133], v189 offset:32768
	ds_read_b128 v[134:137], v189 offset:33792
	ds_read_b128 v[138:141], v189 offset:34816
	ds_read_b128 v[142:145], v189 offset:35840
	s_waitcnt vmcnt(6)
	s_barrier
	v_mfma_f32_16x16x32_bf16 v[54:57], v[194:197], v[158:161], v[54:57]
	v_mfma_f32_16x16x32_bf16 v[50:53], v[202:205], v[158:161], v[50:53]
	v_mfma_f32_16x16x32_bf16 v[38:41], v[194:197], v[166:169], v[38:41]
	v_mfma_f32_16x16x32_bf16 v[34:37], v[202:205], v[166:169], v[34:37]
	v_mfma_f32_16x16x32_bf16 v[22:25], v[194:197], v[176:179], v[22:25]
	v_mfma_f32_16x16x32_bf16 v[18:21], v[202:205], v[176:179], v[18:21]
	v_mfma_f32_16x16x32_bf16 v[6:9], v[194:197], v[184:187], v[6:9]
	v_mfma_f32_16x16x32_bf16 v[2:5], v[202:205], v[184:187], v[2:5]
	v_mfma_f32_16x16x32_bf16 v[54:57], v[198:201], v[162:165], v[54:57]
	v_mfma_f32_16x16x32_bf16 v[50:53], v[206:209], v[162:165], v[50:53]
	v_mfma_f32_16x16x32_bf16 v[38:41], v[198:201], v[172:175], v[38:41]
	v_mfma_f32_16x16x32_bf16 v[34:37], v[206:209], v[172:175], v[34:37]
	v_mfma_f32_16x16x32_bf16 v[22:25], v[198:201], v[180:183], v[22:25]
	v_mfma_f32_16x16x32_bf16 v[18:21], v[206:209], v[180:183], v[18:21]
	v_mfma_f32_16x16x32_bf16 v[6:9], v[198:201], v[190:193], v[6:9]
	v_mfma_f32_16x16x32_bf16 v[2:5], v[206:209], v[190:193], v[2:5]
	s_barrier
	s_add_u32 s92, s92, 0x40000
	s_addc_u32 s93, s93, 0
	s_mov_b32 m0, s43
	ds_read_b128 v[158:161], v171 offset:32768
	ds_read_b128 v[162:165], v171 offset:33792
	ds_read_b128 v[166:169], v171 offset:34816
	ds_read_b128 v[172:175], v171 offset:35840
	ds_read_b128 v[176:179], v171 offset:36864
	ds_read_b128 v[180:183], v171 offset:37888
	ds_read_b128 v[184:187], v171 offset:38912
	ds_read_b128 v[190:193], v171 offset:39936
	global_load_lds_dwordx4 v146, s[92:93]
	s_mov_b32 m0, s44
	s_nop 0
	global_load_lds_dwordx4 v150, s[92:93]
	s_waitcnt lgkmcnt(8)
	s_barrier
	s_waitcnt lgkmcnt(0)
	v_mfma_f32_16x16x32_bf16 v[126:129], v[130:133], v[158:161], v[126:129]
	v_mfma_f32_16x16x32_bf16 v[122:125], v[138:141], v[158:161], v[122:125]
	v_mfma_f32_16x16x32_bf16 v[110:113], v[130:133], v[166:169], v[110:113]
	v_mfma_f32_16x16x32_bf16 v[106:109], v[138:141], v[166:169], v[106:109]
	v_mfma_f32_16x16x32_bf16 v[94:97], v[130:133], v[176:179], v[94:97]
	v_mfma_f32_16x16x32_bf16 v[90:93], v[138:141], v[176:179], v[90:93]
	v_mfma_f32_16x16x32_bf16 v[78:81], v[130:133], v[184:187], v[78:81]
	v_mfma_f32_16x16x32_bf16 v[74:77], v[138:141], v[184:187], v[74:77]
	v_mfma_f32_16x16x32_bf16 v[126:129], v[134:137], v[162:165], v[126:129]
	v_mfma_f32_16x16x32_bf16 v[122:125], v[142:145], v[162:165], v[122:125]
	v_mfma_f32_16x16x32_bf16 v[110:113], v[134:137], v[172:175], v[110:113]
	v_mfma_f32_16x16x32_bf16 v[106:109], v[142:145], v[172:175], v[106:109]
	v_mfma_f32_16x16x32_bf16 v[94:97], v[134:137], v[180:183], v[94:97]
	v_mfma_f32_16x16x32_bf16 v[90:93], v[142:145], v[180:183], v[90:93]
	v_mfma_f32_16x16x32_bf16 v[78:81], v[134:137], v[190:193], v[78:81]
	v_mfma_f32_16x16x32_bf16 v[74:77], v[142:145], v[190:193], v[74:77]
	s_barrier
	s_add_i32 s92, 0, 0x1c000
	s_add_i32 s87, s87, s38
	s_mov_b32 m0, s87
	ds_read_b128 v[194:197], v189 offset:49152
	ds_read_b128 v[198:201], v189 offset:50176
	ds_read_b128 v[202:205], v189 offset:51200
	ds_read_b128 v[206:209], v189 offset:52224
	s_add_u32 s98, s90, s40
	s_addc_u32 s99, s91, s41
	global_load_lds_dwordx4 v148, s[98:99]
	s_add_i32 m0, s87, 0x2000
	s_add_u32 s98, s90, s40
	s_addc_u32 s99, s91, s41
	global_load_lds_dwordx4 v152, s[98:99]
	s_barrier
	s_waitcnt lgkmcnt(0)
	v_mfma_f32_16x16x32_bf16 v[118:121], v[194:197], v[158:161], v[118:121]
	v_mfma_f32_16x16x32_bf16 v[114:117], v[202:205], v[158:161], v[114:117]
	v_mfma_f32_16x16x32_bf16 v[102:105], v[194:197], v[166:169], v[102:105]
	v_mfma_f32_16x16x32_bf16 v[98:101], v[202:205], v[166:169], v[98:101]
	v_mfma_f32_16x16x32_bf16 v[86:89], v[194:197], v[176:179], v[86:89]
	v_mfma_f32_16x16x32_bf16 v[82:85], v[202:205], v[176:179], v[82:85]
	v_mfma_f32_16x16x32_bf16 v[70:73], v[194:197], v[184:187], v[70:73]
	v_mfma_f32_16x16x32_bf16 v[66:69], v[202:205], v[184:187], v[66:69]
	v_mfma_f32_16x16x32_bf16 v[118:121], v[198:201], v[162:165], v[118:121]
	v_mfma_f32_16x16x32_bf16 v[114:117], v[206:209], v[162:165], v[114:117]
	v_mfma_f32_16x16x32_bf16 v[102:105], v[198:201], v[172:175], v[102:105]
	v_mfma_f32_16x16x32_bf16 v[98:101], v[206:209], v[172:175], v[98:101]
	v_mfma_f32_16x16x32_bf16 v[86:89], v[198:201], v[180:183], v[86:89]
	v_mfma_f32_16x16x32_bf16 v[82:85], v[206:209], v[180:183], v[82:85]
	v_mfma_f32_16x16x32_bf16 v[70:73], v[198:201], v[190:193], v[70:73]
	v_mfma_f32_16x16x32_bf16 v[66:69], v[206:209], v[190:193], v[66:69]
	s_mov_b32 m0, s60
	s_barrier
	ds_read_b128 v[158:161], v171 offset:49152
	ds_read_b128 v[162:165], v171 offset:50176
	ds_read_b128 v[166:169], v171 offset:51200
	ds_read_b128 v[172:175], v171 offset:52224
	ds_read_b128 v[176:179], v171 offset:53248
	ds_read_b128 v[180:183], v171 offset:54272
	ds_read_b128 v[184:187], v171 offset:55296
	ds_read_b128 v[190:193], v171 offset:56320
	s_add_u32 s98, s100, s40
	s_addc_u32 s99, s101, s41
	global_load_lds_dwordx4 v146, s[98:99]
	s_mov_b32 m0, s61
	s_add_u32 s98, s100, s40
	s_addc_u32 s99, s101, s41
	global_load_lds_dwordx4 v150, s[98:99]
	s_waitcnt vmcnt(10)
	s_barrier
	s_waitcnt lgkmcnt(0)
	v_mfma_f32_16x16x32_bf16 v[62:65], v[130:133], v[158:161], v[62:65]
	v_mfma_f32_16x16x32_bf16 v[58:61], v[138:141], v[158:161], v[58:61]
	v_mfma_f32_16x16x32_bf16 v[46:49], v[130:133], v[166:169], v[46:49]
	v_mfma_f32_16x16x32_bf16 v[42:45], v[138:141], v[166:169], v[42:45]
	v_mfma_f32_16x16x32_bf16 v[30:33], v[130:133], v[176:179], v[30:33]
	v_mfma_f32_16x16x32_bf16 v[26:29], v[138:141], v[176:179], v[26:29]
	v_mfma_f32_16x16x32_bf16 v[14:17], v[130:133], v[184:187], v[14:17]
	v_mfma_f32_16x16x32_bf16 v[10:13], v[138:141], v[184:187], v[10:13]
	v_mfma_f32_16x16x32_bf16 v[62:65], v[134:137], v[162:165], v[62:65]
	v_mfma_f32_16x16x32_bf16 v[58:61], v[142:145], v[162:165], v[58:61]
	v_mfma_f32_16x16x32_bf16 v[46:49], v[134:137], v[172:175], v[46:49]
	v_mfma_f32_16x16x32_bf16 v[42:45], v[142:145], v[172:175], v[42:45]
	v_mfma_f32_16x16x32_bf16 v[30:33], v[134:137], v[180:183], v[30:33]
	v_mfma_f32_16x16x32_bf16 v[26:29], v[142:145], v[180:183], v[26:29]
	v_mfma_f32_16x16x32_bf16 v[14:17], v[134:137], v[190:193], v[14:17]
	v_mfma_f32_16x16x32_bf16 v[10:13], v[142:145], v[190:193], v[10:13]
	s_barrier
	s_add_u32 s90, s90, 0x40080
	s_addc_u32 s91, s91, 0
	s_add_i32 s87, s92, s38
	s_mov_b32 m0, s87
	s_nop 0
	global_load_lds_dwordx4 v148, s[90:91]
	s_add_i32 m0, s87, 0x2000
	s_nop 0
	global_load_lds_dwordx4 v152, s[90:91]
	s_add_i32 s94, 0, 0x10000
	ds_read_b128 v[130:133], v189
	ds_read_b128 v[134:137], v189 offset:1024
	ds_read_b128 v[138:141], v189 offset:2048
	ds_read_b128 v[142:145], v189 offset:3072
	s_waitcnt vmcnt(6)
	s_barrier
	v_mfma_f32_16x16x32_bf16 v[54:57], v[194:197], v[158:161], v[54:57]
	v_mfma_f32_16x16x32_bf16 v[50:53], v[202:205], v[158:161], v[50:53]
	v_mfma_f32_16x16x32_bf16 v[38:41], v[194:197], v[166:169], v[38:41]
	v_mfma_f32_16x16x32_bf16 v[34:37], v[202:205], v[166:169], v[34:37]
	v_mfma_f32_16x16x32_bf16 v[22:25], v[194:197], v[176:179], v[22:25]
	v_mfma_f32_16x16x32_bf16 v[18:21], v[202:205], v[176:179], v[18:21]
	v_mfma_f32_16x16x32_bf16 v[6:9], v[194:197], v[184:187], v[6:9]
	v_mfma_f32_16x16x32_bf16 v[2:5], v[202:205], v[184:187], v[2:5]
	v_mfma_f32_16x16x32_bf16 v[54:57], v[198:201], v[162:165], v[54:57]
	v_mfma_f32_16x16x32_bf16 v[50:53], v[206:209], v[162:165], v[50:53]
	v_mfma_f32_16x16x32_bf16 v[38:41], v[198:201], v[172:175], v[38:41]
	v_mfma_f32_16x16x32_bf16 v[34:37], v[206:209], v[172:175], v[34:37]
	v_mfma_f32_16x16x32_bf16 v[22:25], v[198:201], v[180:183], v[22:25]
	v_mfma_f32_16x16x32_bf16 v[18:21], v[206:209], v[180:183], v[18:21]
	v_mfma_f32_16x16x32_bf16 v[6:9], v[198:201], v[190:193], v[6:9]
	v_mfma_f32_16x16x32_bf16 v[2:5], v[206:209], v[190:193], v[2:5]
	s_add_i32 s85, s85, 2
	s_add_u32 s88, s88, 0x100
	s_addc_u32 s89, s89, 0
	s_add_u32 s34, s34, 0x100
	s_addc_u32 s79, s79, 0
	s_add_u32 s87, s88, 0xfffc0080
	s_addc_u32 s90, s89, -1
	s_cmp_eq_u32 s85, 12
	s_cselect_b32 s93, s13, s90
	s_cselect_b32 s92, s22, s87
	s_cselect_b32 s91, s7, s79
	s_cselect_b32 s90, s23, s34
	s_cmp_gt_u32 s85, 13
	s_barrier
	s_cbranch_scc0 .LBB0_1209
	s_waitcnt lgkmcnt(0)
	v_mov_b32_e32 v131, v252
	s_lshl_b32 s7, s86, 8
	v_and_b32_e32 v130, 63, v131
	v_or_b32_e32 v0, s72, v130
	v_lshrrev_b32_e32 v0, 1, v0
	v_and_or_b32 v132, v0, 63, s73
	v_add_u32_e32 v134, s7, v132
	v_ashrrev_i32_e32 v135, 31, v134
	v_and_b32_e32 v142, 1, v131
	v_lshlrev_b64 v[134:135], 6, v[134:135]
	v_lshl_add_u64 v[134:135], s[82:83], 0, v[134:135]
	v_lshlrev_b32_e32 v0, 5, v142
	v_lshl_add_u64 v[138:139], v[134:135], 0, v[0:1]
	global_load_dwordx4 v[134:137], v[138:139], off
	s_nop 0
	global_load_dwordx4 v[138:141], v[138:139], off offset:16
	v_lshlrev_b32_e32 v0, 2, v130
	v_cmp_eq_u32_e32 vcc, 0, v142
	s_waitcnt vmcnt(0)
	v_add_f32_e32 v133, v134, v135
	v_add_f32_e32 v134, v136, v137
	v_add_f32_e32 v135, v138, v139
	v_add_f32_e32 v136, v140, v141
	v_add_f32_e32 v133, v133, v134
	v_add_f32_e32 v134, v135, v136
	v_add_f32_e32 v133, v133, v134
	v_xor_b32_e32 v134, 4, v0
	ds_bpermute_b32 v134, v134, v133
	s_and_saveexec_b64 s[22:23], vcc
	s_cbranch_execz .LBB0_1212
	s_waitcnt lgkmcnt(0)
	v_add_f32_e32 v133, v133, v134
	v_fmamk_f32 v133, v133, 0x3a800000, v224
	s_mov_b32 s13, 0x800000
	v_mul_f32_e32 v134, 0x4b800000, v133
	v_cmp_gt_f32_e32 vcc, s13, v133
	v_lshl_add_u32 v132, v132, 2, 0
	v_add_u32_e32 v132, 0x20000, v132
	v_cndmask_b32_e32 v133, v133, v134, vcc
	v_rsq_f32_e32 v133, v133
	s_nop 0
	v_mul_f32_e32 v134, 0x45800000, v133
	v_cndmask_b32_e32 v133, v133, v134, vcc
	ds_write_b32 v132, v133
